# k11 plus first K-loop iteration peeled with zero srcC MFMAs; 128 accumulator-zeroing moves per tile removed
# speedup vs baseline: 1.0139x; 1.0009x over previous
;     __device__ bool next(int i, Unit& u) const { if (i >= 2) return false; const int x = c & 7, j = c >> 3; u.pm = 32 * i + 4 * x + (j & 3); u.pn = j >> 2; return true; }
; #define PG8_STAGE(bufoff, gbase, voff) do { _Pragma("unroll") for (int _i = 0; _i < 2; ++_i) \
;         __builtin_amdgcn_global_load_lds((const unsigned*)((const char*)(gbase) + (voff)[_i]), (LAS unsigned*)(lds + (bufoff) + ldsw + _i * 8192), 16, 0, 0); } while (0)
; #define PG8_LDA(dst, b, h) do { _Pragma("unroll") for (int m = 0; m < 4; ++m) _Pragma("unroll") for (int k = 0; k < 2; ++k) dst[m][k] = *(const LAS bf16x8*)(lds + PG8_SA(b, h) + aoff + m * 2048 + k * 1024); } while (0)
; #define PG8_LDB(dst, b, h) do { _Pragma("unroll") for (int n = 0; n < 2; ++n) _Pragma("unroll") for (int k = 0; k < 2; ++k) dst[n][k] = *(const LAS bf16x8*)(lds + PG8_SB(b, h) + boff + n * 2048 + k * 1024); } while (0)
; #define PG8_WAIT_V(n) asm volatile("s_waitcnt vmcnt(" #n ")" ::: "memory")
; #define PG8_WAIT_L(n) asm volatile("s_waitcnt lgkmcnt(" #n ")" ::: "memory")
; #define PG8_BAR __builtin_amdgcn_s_barrier()
; template <class Epi, class Sched, bool ALIGN_EPI = true>
; __device__ __forceinline__ void gemm_phase(LAS unsigned char* lds, const Gemm g, const Sched& S, const Epi& E) {
;     ...
;         const bool has_next = S.next(ui + 1, nxt);
;         const char* nA = has_next ? (const char*)g.A + ((size_t)nxt.pm * BM * g.lda + (size_t)nxt.pn * g.a_pn_off) * 2 : cA; const char* nB = has_next ? (const char*)g.Bt + (size_t)nxt.pn * BM * g.ldb * 2 : cB;
;         for (int t = 0; t < nt; t += 2) {
;             const bool last = (t == nt - 2);
;             const char* a1 = cA + (size_t)(t + 1) * kstep;
;             const char* a2 = last ? nA : cA + (size_t)(t + 2) * kstep; const char* b2 = last ? nB : cB + (size_t)(t + 2) * kstep;
;             const char* a3 = a2 + kstep; const char* b3 = b2 + kstep;
;             PG8_LDB(B0, 0, 0); PG8_LDB(B1, 0, 1); PG8_SCHED; PG8_LDA(At, 0, 0); PG8_STAGE(PG8_SA(1, 1), a1 + hA, voffA);
;             PG8_WAIT_V(8); PG8_WAIT_L(0); PG8_BAR; PG8_MMA(0, 0, At, B0); PG8_MMA(0, 1, At, B1); PG8_BAR; PG8_SCHED;
;             PG8_LDA(At, 0, 1); PG8_STAGE(PG8_SB(0, 0), b2, voffB); PG8_STAGE(PG8_SB(0, 1), b2 + hB, voffB); PG8_STAGE(PG8_SA(0, 0), a2, voffA);
;             PG8_WAIT_V(8); PG8_WAIT_L(0); PG8_BAR; PG8_MMA(1, 0, At, B0); PG8_MMA(1, 1, At, B1); PG8_BAR; PG8_SCHED;
.LBB0_76:
	s_ashr_i32 s15, s14, 31
	s_lshl_b64 s[18:19], s[14:15], 20
	s_add_u32 s38, s46, s18
	s_addc_u32 s39, s47, s19
	s_and_b64 s[18:19], s[4:5], exec
	s_cselect_b32 s15, s39, s7
	s_cselect_b32 s17, s38, s6
	s_ashr_i32 s13, s12, 31
	s_lshl_b64 s[18:19], s[12:13], 20
	s_add_u32 s40, s53, s18
	s_addc_u32 s41, s58, s19
	s_and_b64 s[18:19], s[4:5], exec
	s_cselect_b32 s13, s41, s43
	s_cselect_b32 s18, s40, s42
	s_add_u32 s6, s6, 0x80080
	s_addc_u32 s7, s7, 0
	s_add_u32 s19, s42, 0x100
	s_addc_u32 s24, s43, 0
	s_mov_b32 s25, -2
	s_add_u32 s26, s6, 0xfff80080
	s_addc_u32 s27, s7, -1
	s_add_i32 s30, 0, 0x10000
	s_cmp_eq_u32 s25, 28
	s_cselect_b32 s45, s15, s27
	s_cselect_b32 s44, s17, s26
	s_cselect_b32 s43, s13, s24
	s_cselect_b32 s42, s18, s19
	s_add_i32 s31, 0, 0x14000
	v_add_u32_e32 v144, s30, v166
	v_add_u32_e32 v156, s31, v166
	ds_read_b128 v[132:135], v144
	ds_read_b128 v[136:139], v144 offset:1024
	ds_read_b128 v[140:143], v144 offset:2048
	ds_read_b128 v[144:147], v144 offset:3072
	ds_read_b128 v[170:173], v156
	ds_read_b128 v[174:177], v156 offset:1024
	ds_read_b128 v[178:181], v156 offset:2048
	ds_read_b128 v[182:185], v156 offset:3072
	v_lshl_add_u64 v[156:157], s[6:7], 0, v[152:153]
	s_add_i32 m0, s60, 0xc000
	ds_read_b128 v[186:189], v168
	ds_read_b128 v[190:193], v168 offset:1024
	ds_read_b128 v[194:197], v168 offset:2048
	ds_read_b128 v[204:207], v168 offset:3072
	ds_read_b128 v[208:211], v168 offset:4096
	ds_read_b128 v[212:215], v168 offset:5120
	ds_read_b128 v[216:219], v168 offset:6144
	ds_read_b128 v[220:223], v168 offset:7168
	global_load_lds_dwordx4 v[156:157], off
	v_lshl_add_u64 v[156:157], s[6:7], 0, v[154:155]
	s_add_i32 m0, s60, 0xe000
	s_nop 0
	global_load_lds_dwordx4 v[156:157], off
	s_waitcnt vmcnt(8)
	s_waitcnt lgkmcnt(0)
	s_barrier
	s_setprio 1
	s_waitcnt lgkmcnt(0)
	v_mfma_f32_16x16x32_bf16 v[128:131], v[132:135], v[186:189], 0
	v_mfma_f32_16x16x32_bf16 v[128:131], v[136:139], v[190:193], v[128:131]
	v_mfma_f32_16x16x32_bf16 v[124:127], v[140:143], v[186:189], 0
	v_mfma_f32_16x16x32_bf16 v[124:127], v[144:147], v[190:193], v[124:127]
	v_mfma_f32_16x16x32_bf16 v[116:119], v[132:135], v[194:197], 0
	v_mfma_f32_16x16x32_bf16 v[116:119], v[136:139], v[204:207], v[116:119]
	v_mfma_f32_16x16x32_bf16 v[112:115], v[140:143], v[194:197], 0
	v_mfma_f32_16x16x32_bf16 v[112:115], v[144:147], v[204:207], v[112:115]
	v_mfma_f32_16x16x32_bf16 v[104:107], v[132:135], v[208:211], 0
	v_mfma_f32_16x16x32_bf16 v[104:107], v[136:139], v[212:215], v[104:107]
	v_mfma_f32_16x16x32_bf16 v[96:99], v[140:143], v[208:211], 0
	v_mfma_f32_16x16x32_bf16 v[96:99], v[144:147], v[212:215], v[96:99]
	v_mfma_f32_16x16x32_bf16 v[88:91], v[132:135], v[216:219], 0
	v_mfma_f32_16x16x32_bf16 v[88:91], v[136:139], v[220:223], v[88:91]
	v_mfma_f32_16x16x32_bf16 v[80:83], v[140:143], v[216:219], 0
	v_mfma_f32_16x16x32_bf16 v[80:83], v[144:147], v[220:223], v[80:83]
	s_setprio 0
	s_setprio 1
	v_mfma_f32_16x16x32_bf16 v[120:123], v[170:173], v[186:189], 0
	v_mfma_f32_16x16x32_bf16 v[120:123], v[174:177], v[190:193], v[120:123]
	v_mfma_f32_16x16x32_bf16 v[108:111], v[178:181], v[186:189], 0
	v_mfma_f32_16x16x32_bf16 v[108:111], v[182:185], v[190:193], v[108:111]
	v_mfma_f32_16x16x32_bf16 v[100:103], v[170:173], v[194:197], 0
	v_mfma_f32_16x16x32_bf16 v[100:103], v[174:177], v[204:207], v[100:103]
	v_mfma_f32_16x16x32_bf16 v[92:95], v[178:181], v[194:197], 0
	v_mfma_f32_16x16x32_bf16 v[92:95], v[182:185], v[204:207], v[92:95]
	v_mfma_f32_16x16x32_bf16 v[84:87], v[170:173], v[208:211], 0
	v_mfma_f32_16x16x32_bf16 v[84:87], v[174:177], v[212:215], v[84:87]
	v_mfma_f32_16x16x32_bf16 v[76:79], v[178:181], v[208:211], 0
	v_mfma_f32_16x16x32_bf16 v[76:79], v[182:185], v[212:215], v[76:79]
	s_setprio 2
	s_barrier
	v_mfma_f32_16x16x32_bf16 v[72:75], v[170:173], v[216:219], 0
	v_mfma_f32_16x16x32_bf16 v[72:75], v[174:177], v[220:223], v[72:75]
	v_mfma_f32_16x16x32_bf16 v[68:71], v[178:181], v[216:219], 0
	v_mfma_f32_16x16x32_bf16 v[68:71], v[182:185], v[220:223], v[68:71]
	s_setprio 0
	s_add_i32 s26, s30, s59
	v_lshl_add_u64 v[156:157], s[42:43], 0, v[2:3]
	s_mov_b32 m0, s26
	ds_read_b128 v[186:189], v168 offset:16384
	ds_read_b128 v[190:193], v168 offset:17408
	ds_read_b128 v[194:197], v168 offset:18432
	ds_read_b128 v[204:207], v168 offset:19456
	ds_read_b128 v[208:211], v168 offset:20480
	ds_read_b128 v[212:215], v168 offset:21504
	ds_read_b128 v[216:219], v168 offset:22528
	ds_read_b128 v[220:223], v168 offset:23552
	global_load_lds_dwordx4 v[156:157], off
	s_add_i32 m0, s26, 0x2000
	s_add_u32 s26, s42, 0x80000
	v_lshl_add_u64 v[164:165], s[42:43], 0, v[0:1]
	s_addc_u32 s27, s43, 0
	s_add_i32 s30, s31, s59
	global_load_lds_dwordx4 v[164:165], off
	v_lshl_add_u64 v[224:225], s[26:27], 0, v[2:3]
	s_mov_b32 m0, s30
	v_lshl_add_u64 v[226:227], s[44:45], 0, v[148:149]
	global_load_lds_dwordx4 v[224:225], off
	v_lshl_add_u64 v[224:225], s[26:27], 0, v[0:1]
	s_add_i32 m0, s30, 0x2000
	s_nop 0
	global_load_lds_dwordx4 v[224:225], off
	v_lshl_add_u64 v[224:225], s[44:45], 0, v[150:151]
	s_mov_b32 m0, s60
	s_nop 0
	global_load_lds_dwordx4 v[224:225], off
	s_mov_b32 m0, s61
	s_nop 0
	global_load_lds_dwordx4 v[226:227], off
	s_waitcnt vmcnt(8)
	s_waitcnt lgkmcnt(0)
	s_barrier
; #define PG8_STAGE(bufoff, gbase, voff) do { _Pragma("unroll") for (int _i = 0; _i < 2; ++_i) \
;         __builtin_amdgcn_global_load_lds((const unsigned*)((const char*)(gbase) + (voff)[_i]), (LAS unsigned*)(lds + (bufoff) + ldsw + _i * 8192), 16, 0, 0); } while (0)
; #define PG8_LDA(dst, b, h) do { _Pragma("unroll") for (int m = 0; m < 4; ++m) _Pragma("unroll") for (int k = 0; k < 2; ++k) dst[m][k] = *(const LAS bf16x8*)(lds + PG8_SA(b, h) + aoff + m * 2048 + k * 1024); } while (0)
; #define PG8_LDB(dst, b, h) do { _Pragma("unroll") for (int n = 0; n < 2; ++n) _Pragma("unroll") for (int k = 0; k < 2; ++k) dst[n][k] = *(const LAS bf16x8*)(lds + PG8_SB(b, h) + boff + n * 2048 + k * 1024); } while (0)
; #define PG8_MMA(ai, bj, At, Bt) do { __builtin_amdgcn_s_setprio(1); _Pragma("unroll") for (int m = 0; m < 4; ++m) _Pragma("unroll") for (int n = 0; n < 2; ++n) _Pragma("unroll") for (int k = 0; k < 2; ++k) \
;         acc[ai][bj][m][n] = __builtin_amdgcn_mfma_f32_16x16x32_bf16(Bt[n][k], At[m][k], acc[ai][bj][m][n], 0, 0, 0); __builtin_amdgcn_s_setprio(0); } while (0)
; #define PG8_WAIT_V(n) asm volatile("s_waitcnt vmcnt(" #n ")" ::: "memory")
; #define PG8_WAIT_L(n) asm volatile("s_waitcnt lgkmcnt(" #n ")" ::: "memory")
; #define PG8_BAR __builtin_amdgcn_s_barrier()
; #define PG8_SCHED __builtin_amdgcn_sched_barrier(0)
; template <class Epi, class Sched, bool ALIGN_EPI = true>
; __device__ __forceinline__ void gemm_phase(LAS unsigned char* lds, const Gemm g, const Sched& S, const Epi& E) {
;     ...
;             PG8_WAIT_V(8); PG8_WAIT_L(0); PG8_BAR; PG8_MMA(1, 0, At, B0); PG8_MMA(1, 1, At, B1); PG8_BAR; PG8_SCHED;
;             PG8_LDB(B0, 1, 0); PG8_LDB(B1, 1, 1); PG8_SCHED; PG8_LDA(At, 1, 0); PG8_STAGE(PG8_SA(0, 1), a2 + hA, voffA);
;             PG8_WAIT_V(8); PG8_WAIT_L(0); PG8_BAR; PG8_MMA(0, 0, At, B0); PG8_MMA(0, 1, At, B1); PG8_BAR; PG8_SCHED;
	s_setprio 1
	s_waitcnt lgkmcnt(0)
	v_mfma_f32_16x16x32_bf16 v[64:67], v[132:135], v[186:189], 0
	v_mfma_f32_16x16x32_bf16 v[64:67], v[136:139], v[190:193], v[64:67]
	v_mfma_f32_16x16x32_bf16 v[60:63], v[140:143], v[186:189], 0
	v_mfma_f32_16x16x32_bf16 v[60:63], v[144:147], v[190:193], v[60:63]
	v_mfma_f32_16x16x32_bf16 v[56:59], v[132:135], v[194:197], 0
	v_mfma_f32_16x16x32_bf16 v[56:59], v[136:139], v[204:207], v[56:59]
	v_mfma_f32_16x16x32_bf16 v[48:51], v[140:143], v[194:197], 0
	v_mfma_f32_16x16x32_bf16 v[48:51], v[144:147], v[204:207], v[48:51]
	v_mfma_f32_16x16x32_bf16 v[40:43], v[132:135], v[208:211], 0
	v_mfma_f32_16x16x32_bf16 v[40:43], v[136:139], v[212:215], v[40:43]
	v_mfma_f32_16x16x32_bf16 v[32:35], v[140:143], v[208:211], 0
	v_mfma_f32_16x16x32_bf16 v[32:35], v[144:147], v[212:215], v[32:35]
	v_mfma_f32_16x16x32_bf16 v[24:27], v[132:135], v[216:219], 0
	v_mfma_f32_16x16x32_bf16 v[24:27], v[136:139], v[220:223], v[24:27]
	v_mfma_f32_16x16x32_bf16 v[16:19], v[140:143], v[216:219], 0
	v_mfma_f32_16x16x32_bf16 v[16:19], v[144:147], v[220:223], v[16:19]
	s_setprio 0
	s_setprio 1
	v_mfma_f32_16x16x32_bf16 v[52:55], v[170:173], v[186:189], 0
	v_mfma_f32_16x16x32_bf16 v[52:55], v[174:177], v[190:193], v[52:55]
	v_mfma_f32_16x16x32_bf16 v[44:47], v[178:181], v[186:189], 0
	v_mfma_f32_16x16x32_bf16 v[44:47], v[182:185], v[190:193], v[44:47]
	v_mfma_f32_16x16x32_bf16 v[36:39], v[170:173], v[194:197], 0
	v_mfma_f32_16x16x32_bf16 v[36:39], v[174:177], v[204:207], v[36:39]
	v_mfma_f32_16x16x32_bf16 v[28:31], v[178:181], v[194:197], 0
	v_mfma_f32_16x16x32_bf16 v[28:31], v[182:185], v[204:207], v[28:31]
	v_mfma_f32_16x16x32_bf16 v[20:23], v[170:173], v[208:211], 0
	v_mfma_f32_16x16x32_bf16 v[20:23], v[174:177], v[212:215], v[20:23]
	v_mfma_f32_16x16x32_bf16 v[12:15], v[178:181], v[208:211], 0
	v_mfma_f32_16x16x32_bf16 v[12:15], v[182:185], v[212:215], v[12:15]
	s_setprio 2
	s_barrier
	v_mfma_f32_16x16x32_bf16 v[8:11], v[170:173], v[216:219], 0
	v_mfma_f32_16x16x32_bf16 v[8:11], v[174:177], v[220:223], v[8:11]
	v_mfma_f32_16x16x32_bf16 v[4:7], v[178:181], v[216:219], 0
	v_mfma_f32_16x16x32_bf16 v[4:7], v[182:185], v[220:223], v[4:7]
	s_setprio 0
	s_add_i32 s30, 0, 0x18000
	s_add_i32 s31, 0, 0x1c000
	v_add_u32_e32 v144, s30, v166
	v_add_u32_e32 v160, s31, v166
	ds_read_b128 v[132:135], v144
	ds_read_b128 v[136:139], v144 offset:1024
	ds_read_b128 v[140:143], v144 offset:2048
	ds_read_b128 v[144:147], v144 offset:3072
	ds_read_b128 v[170:173], v160
	ds_read_b128 v[174:177], v160 offset:1024
	ds_read_b128 v[178:181], v160 offset:2048
	ds_read_b128 v[182:185], v160 offset:3072
	s_add_u32 s26, s44, 0x80000
	s_addc_u32 s27, s45, 0
	s_mov_b32 m0, s62
	v_lshl_add_u64 v[228:229], s[26:27], 0, v[150:151]
	ds_read_b128 v[186:189], v168 offset:32768
	ds_read_b128 v[190:193], v168 offset:33792
	ds_read_b128 v[194:197], v168 offset:34816
	ds_read_b128 v[204:207], v168 offset:35840
	ds_read_b128 v[208:211], v168 offset:36864
	ds_read_b128 v[212:215], v168 offset:37888
	ds_read_b128 v[216:219], v168 offset:38912
	ds_read_b128 v[220:223], v168 offset:39936
	global_load_lds_dwordx4 v[228:229], off
	v_lshl_add_u64 v[228:229], s[26:27], 0, v[148:149]
	s_mov_b32 m0, s63
	s_nop 0
	global_load_lds_dwordx4 v[228:229], off
	s_waitcnt vmcnt(8)
	s_waitcnt lgkmcnt(0)
	s_barrier
	s_setprio 1
	s_waitcnt lgkmcnt(0)
	v_mfma_f32_16x16x32_bf16 v[128:131], v[132:135], v[186:189], v[128:131]
	v_mfma_f32_16x16x32_bf16 v[128:131], v[136:139], v[190:193], v[128:131]
	v_mfma_f32_16x16x32_bf16 v[124:127], v[140:143], v[186:189], v[124:127]
	v_mfma_f32_16x16x32_bf16 v[124:127], v[144:147], v[190:193], v[124:127]
	v_mfma_f32_16x16x32_bf16 v[116:119], v[132:135], v[194:197], v[116:119]
	v_mfma_f32_16x16x32_bf16 v[116:119], v[136:139], v[204:207], v[116:119]
	v_mfma_f32_16x16x32_bf16 v[112:115], v[140:143], v[194:197], v[112:115]
	v_mfma_f32_16x16x32_bf16 v[112:115], v[144:147], v[204:207], v[112:115]
	v_mfma_f32_16x16x32_bf16 v[104:107], v[132:135], v[208:211], v[104:107]
	v_mfma_f32_16x16x32_bf16 v[104:107], v[136:139], v[212:215], v[104:107]
	v_mfma_f32_16x16x32_bf16 v[96:99], v[140:143], v[208:211], v[96:99]
	v_mfma_f32_16x16x32_bf16 v[96:99], v[144:147], v[212:215], v[96:99]
	v_mfma_f32_16x16x32_bf16 v[88:91], v[132:135], v[216:219], v[88:91]
	v_mfma_f32_16x16x32_bf16 v[88:91], v[136:139], v[220:223], v[88:91]
	v_mfma_f32_16x16x32_bf16 v[80:83], v[140:143], v[216:219], v[80:83]
	v_mfma_f32_16x16x32_bf16 v[80:83], v[144:147], v[220:223], v[80:83]
	s_setprio 0
	s_setprio 1
	v_mfma_f32_16x16x32_bf16 v[120:123], v[170:173], v[186:189], v[120:123]
	v_mfma_f32_16x16x32_bf16 v[120:123], v[174:177], v[190:193], v[120:123]
	v_mfma_f32_16x16x32_bf16 v[108:111], v[178:181], v[186:189], v[108:111]
	v_mfma_f32_16x16x32_bf16 v[108:111], v[182:185], v[190:193], v[108:111]
	v_mfma_f32_16x16x32_bf16 v[100:103], v[170:173], v[194:197], v[100:103]
	v_mfma_f32_16x16x32_bf16 v[100:103], v[174:177], v[204:207], v[100:103]
	v_mfma_f32_16x16x32_bf16 v[92:95], v[178:181], v[194:197], v[92:95]
	v_mfma_f32_16x16x32_bf16 v[92:95], v[182:185], v[204:207], v[92:95]
	v_mfma_f32_16x16x32_bf16 v[84:87], v[170:173], v[208:211], v[84:87]
	v_mfma_f32_16x16x32_bf16 v[84:87], v[174:177], v[212:215], v[84:87]
	v_mfma_f32_16x16x32_bf16 v[76:79], v[178:181], v[208:211], v[76:79]
	v_mfma_f32_16x16x32_bf16 v[76:79], v[182:185], v[212:215], v[76:79]
	s_setprio 2
	s_barrier
; #define PG8_STAGE(bufoff, gbase, voff) do { _Pragma("unroll") for (int _i = 0; _i < 2; ++_i) \
;         __builtin_amdgcn_global_load_lds((const unsigned*)((const char*)(gbase) + (voff)[_i]), (LAS unsigned*)(lds + (bufoff) + ldsw + _i * 8192), 16, 0, 0); } while (0)
; #define PG8_LDA(dst, b, h) do { _Pragma("unroll") for (int m = 0; m < 4; ++m) _Pragma("unroll") for (int k = 0; k < 2; ++k) dst[m][k] = *(const LAS bf16x8*)(lds + PG8_SA(b, h) + aoff + m * 2048 + k * 1024); } while (0)
; #define PG8_MMA(ai, bj, At, Bt) do { __builtin_amdgcn_s_setprio(1); _Pragma("unroll") for (int m = 0; m < 4; ++m) _Pragma("unroll") for (int n = 0; n < 2; ++n) _Pragma("unroll") for (int k = 0; k < 2; ++k) \
;         acc[ai][bj][m][n] = __builtin_amdgcn_mfma_f32_16x16x32_bf16(Bt[n][k], At[m][k], acc[ai][bj][m][n], 0, 0, 0); __builtin_amdgcn_s_setprio(0); } while (0)
; #define PG8_WAIT_V(n) asm volatile("s_waitcnt vmcnt(" #n ")" ::: "memory")
; #define PG8_WAIT_L(n) asm volatile("s_waitcnt lgkmcnt(" #n ")" ::: "memory")
; #define PG8_BAR __builtin_amdgcn_s_barrier()
; #define PG8_SCHED __builtin_amdgcn_sched_barrier(0)
; template <class Epi, class Sched, bool ALIGN_EPI = true>
; __device__ __forceinline__ void gemm_phase(LAS unsigned char* lds, const Gemm g, const Sched& S, const Epi& E) {
;     ...
;             PG8_WAIT_V(8); PG8_WAIT_L(0); PG8_BAR; PG8_MMA(0, 0, At, B0); PG8_MMA(0, 1, At, B1); PG8_BAR; PG8_SCHED;
;             PG8_LDA(At, 1, 1); PG8_STAGE(PG8_SB(1, 0), b3, voffB); PG8_STAGE(PG8_SB(1, 1), b3 + hB, voffB); PG8_STAGE(PG8_SA(1, 0), a3, voffA);
;             PG8_WAIT_V(8); PG8_WAIT_L(0); PG8_BAR; PG8_MMA(1, 0, At, B0); PG8_MMA(1, 1, At, B1); PG8_BAR; PG8_SCHED;
;         }
	v_mfma_f32_16x16x32_bf16 v[72:75], v[170:173], v[216:219], v[72:75]
	v_mfma_f32_16x16x32_bf16 v[72:75], v[174:177], v[220:223], v[72:75]
	v_mfma_f32_16x16x32_bf16 v[68:71], v[178:181], v[216:219], v[68:71]
	v_mfma_f32_16x16x32_bf16 v[68:71], v[182:185], v[220:223], v[68:71]
	s_setprio 0
	s_add_i32 s26, s30, s59
	v_lshl_add_u64 v[156:157], v[156:157], 0, s[86:87]
	s_mov_b32 m0, s26
	ds_read_b128 v[186:189], v168 offset:49152
	ds_read_b128 v[190:193], v168 offset:50176
	ds_read_b128 v[194:197], v168 offset:51200
	ds_read_b128 v[204:207], v168 offset:52224
	ds_read_b128 v[208:211], v168 offset:53248
	ds_read_b128 v[212:215], v168 offset:54272
	ds_read_b128 v[216:219], v168 offset:55296
	ds_read_b128 v[220:223], v168 offset:56320
	global_load_lds_dwordx4 v[156:157], off
	s_add_i32 m0, s26, 0x2000
	s_add_u32 s26, s42, 0x80080
	v_lshl_add_u64 v[156:157], v[164:165], 0, s[86:87]
	s_addc_u32 s27, s43, 0
	s_add_i32 s30, s31, s59
	global_load_lds_dwordx4 v[156:157], off
	v_lshl_add_u64 v[156:157], s[26:27], 0, v[2:3]
	s_mov_b32 m0, s30
	s_nop 0
	global_load_lds_dwordx4 v[156:157], off
	v_lshl_add_u64 v[156:157], s[26:27], 0, v[0:1]
	s_add_i32 m0, s30, 0x2000
	s_nop 0
	global_load_lds_dwordx4 v[156:157], off
	v_lshl_add_u64 v[156:157], v[224:225], 0, s[86:87]
	s_mov_b32 m0, s64
	s_nop 0
	global_load_lds_dwordx4 v[156:157], off
	v_lshl_add_u64 v[156:157], v[226:227], 0, s[86:87]
	s_mov_b32 m0, s65
	s_nop 0
	global_load_lds_dwordx4 v[156:157], off
	s_waitcnt vmcnt(8)
	s_waitcnt lgkmcnt(0)
	s_barrier
	s_setprio 1
	s_waitcnt lgkmcnt(0)
	v_mfma_f32_16x16x32_bf16 v[64:67], v[132:135], v[186:189], v[64:67]
	v_mfma_f32_16x16x32_bf16 v[64:67], v[136:139], v[190:193], v[64:67]
	v_mfma_f32_16x16x32_bf16 v[60:63], v[140:143], v[186:189], v[60:63]
	v_mfma_f32_16x16x32_bf16 v[60:63], v[144:147], v[190:193], v[60:63]
	v_mfma_f32_16x16x32_bf16 v[56:59], v[132:135], v[194:197], v[56:59]
	v_mfma_f32_16x16x32_bf16 v[56:59], v[136:139], v[204:207], v[56:59]
	v_mfma_f32_16x16x32_bf16 v[48:51], v[140:143], v[194:197], v[48:51]
	v_mfma_f32_16x16x32_bf16 v[48:51], v[144:147], v[204:207], v[48:51]
	v_mfma_f32_16x16x32_bf16 v[40:43], v[132:135], v[208:211], v[40:43]
	v_mfma_f32_16x16x32_bf16 v[40:43], v[136:139], v[212:215], v[40:43]
	v_mfma_f32_16x16x32_bf16 v[32:35], v[140:143], v[208:211], v[32:35]
	v_mfma_f32_16x16x32_bf16 v[32:35], v[144:147], v[212:215], v[32:35]
	v_mfma_f32_16x16x32_bf16 v[24:27], v[132:135], v[216:219], v[24:27]
	v_mfma_f32_16x16x32_bf16 v[24:27], v[136:139], v[220:223], v[24:27]
	v_mfma_f32_16x16x32_bf16 v[16:19], v[140:143], v[216:219], v[16:19]
	v_mfma_f32_16x16x32_bf16 v[16:19], v[144:147], v[220:223], v[16:19]
	s_setprio 0
	s_setprio 1
	v_mfma_f32_16x16x32_bf16 v[52:55], v[170:173], v[186:189], v[52:55]
	v_mfma_f32_16x16x32_bf16 v[52:55], v[174:177], v[190:193], v[52:55]
	v_mfma_f32_16x16x32_bf16 v[44:47], v[178:181], v[186:189], v[44:47]
	v_mfma_f32_16x16x32_bf16 v[44:47], v[182:185], v[190:193], v[44:47]
	v_mfma_f32_16x16x32_bf16 v[36:39], v[170:173], v[194:197], v[36:39]
	v_mfma_f32_16x16x32_bf16 v[36:39], v[174:177], v[204:207], v[36:39]
	v_mfma_f32_16x16x32_bf16 v[28:31], v[178:181], v[194:197], v[28:31]
	v_mfma_f32_16x16x32_bf16 v[28:31], v[182:185], v[204:207], v[28:31]
	v_mfma_f32_16x16x32_bf16 v[20:23], v[170:173], v[208:211], v[20:23]
	v_mfma_f32_16x16x32_bf16 v[20:23], v[174:177], v[212:215], v[20:23]
	v_mfma_f32_16x16x32_bf16 v[12:15], v[178:181], v[208:211], v[12:15]
	v_mfma_f32_16x16x32_bf16 v[12:15], v[182:185], v[212:215], v[12:15]
	s_setprio 2
	s_barrier
	v_mfma_f32_16x16x32_bf16 v[8:11], v[170:173], v[216:219], v[8:11]
	v_mfma_f32_16x16x32_bf16 v[8:11], v[174:177], v[220:223], v[8:11]
	v_mfma_f32_16x16x32_bf16 v[4:7], v[178:181], v[216:219], v[4:7]
	v_mfma_f32_16x16x32_bf16 v[4:7], v[182:185], v[220:223], v[4:7]
	s_setprio 0
	s_add_i32 s25, s25, 2
	s_add_u32 s6, s6, 0x100
	s_addc_u32 s7, s7, 0
	s_add_u32 s19, s19, 0x100
	s_addc_u32 s24, s24, 0
	s_cmp_gt_u32 s25, 29
	s_cbranch_scc1 .Lpeel_exit_77

; #define PG8_BAR __builtin_amdgcn_s_barrier()
; template <class Epi, class Sched, bool ALIGN_EPI = true>
; __device__ __forceinline__ void gemm_phase(LAS unsigned char* lds, const Gemm g, const Sched& S, const Epi& E) {
;     ...
;         if constexpr (ALIGN_EPI) { if (wr == 0) PG8_BAR; }
.Lpeel_exit_77:
	s_and_b64 vcc, exec, s[10:11]
	s_cbranch_vccz .LBB0_80
	s_barrier

;     __device__ bool next(int i, Unit& u) const { if (i >= 2) return false; const int x = c & 7, j = c >> 3; u.pm = 32 * i + 4 * x + (j & 3); u.pn = j >> 2; return true; }
; #define PG8_STAGE(bufoff, gbase, voff) do { _Pragma("unroll") for (int _i = 0; _i < 2; ++_i) \
;         __builtin_amdgcn_global_load_lds((const unsigned*)((const char*)(gbase) + (voff)[_i]), (LAS unsigned*)(lds + (bufoff) + ldsw + _i * 8192), 16, 0, 0); } while (0)
; #define PG8_LDA(dst, b, h) do { _Pragma("unroll") for (int m = 0; m < 4; ++m) _Pragma("unroll") for (int k = 0; k < 2; ++k) dst[m][k] = *(const LAS bf16x8*)(lds + PG8_SA(b, h) + aoff + m * 2048 + k * 1024); } while (0)
; #define PG8_LDB(dst, b, h) do { _Pragma("unroll") for (int n = 0; n < 2; ++n) _Pragma("unroll") for (int k = 0; k < 2; ++k) dst[n][k] = *(const LAS bf16x8*)(lds + PG8_SB(b, h) + boff + n * 2048 + k * 1024); } while (0)
; #define PG8_WAIT_V(n) asm volatile("s_waitcnt vmcnt(" #n ")" ::: "memory")
; #define PG8_WAIT_L(n) asm volatile("s_waitcnt lgkmcnt(" #n ")" ::: "memory")
; #define PG8_BAR __builtin_amdgcn_s_barrier()
; template <class Epi, class Sched, bool ALIGN_EPI = true>
; __device__ __forceinline__ void gemm_phase(LAS unsigned char* lds, const Gemm g, const Sched& S, const Epi& E) {
;     ...
;         const bool has_next = S.next(ui + 1, nxt);
;         const char* nA = has_next ? (const char*)g.A + ((size_t)nxt.pm * BM * g.lda + (size_t)nxt.pn * g.a_pn_off) * 2 : cA; const char* nB = has_next ? (const char*)g.Bt + (size_t)nxt.pn * BM * g.ldb * 2 : cB;
;         for (int t = 0; t < nt; t += 2) {
;             const bool last = (t == nt - 2);
;             const char* a1 = cA + (size_t)(t + 1) * kstep;
;             const char* a2 = last ? nA : cA + (size_t)(t + 2) * kstep; const char* b2 = last ? nB : cB + (size_t)(t + 2) * kstep;
;             const char* a3 = a2 + kstep; const char* b3 = b2 + kstep;
;             PG8_LDB(B0, 0, 0); PG8_LDB(B1, 0, 1); PG8_SCHED; PG8_LDA(At, 0, 0); PG8_STAGE(PG8_SA(1, 1), a1 + hA, voffA);
;             PG8_WAIT_V(8); PG8_WAIT_L(0); PG8_BAR; PG8_MMA(0, 0, At, B0); PG8_MMA(0, 1, At, B1); PG8_BAR; PG8_SCHED;
;             PG8_LDA(At, 0, 1); PG8_STAGE(PG8_SB(0, 0), b2, voffB); PG8_STAGE(PG8_SB(0, 1), b2 + hB, voffB); PG8_STAGE(PG8_SA(0, 0), a2, voffA);
;             PG8_WAIT_V(8); PG8_WAIT_L(0); PG8_BAR; PG8_MMA(1, 0, At, B0); PG8_MMA(1, 1, At, B1); PG8_BAR; PG8_SCHED;
.LBB0_217:
	s_ashr_i32 s11, s10, 31
	s_lshl_b64 s[12:13], s[10:11], 20
	s_add_u32 s12, s46, s12
	s_addc_u32 s13, s47, s13
	s_and_b64 s[14:15], s[4:5], exec
	s_cselect_b32 s11, s13, s39
	s_cselect_b32 s18, s12, s38
	s_ashr_i32 s9, s8, 31
	s_lshl_b64 s[14:15], s[8:9], 20
	s_add_u32 s14, s44, s14
	s_addc_u32 s15, s45, s15
	s_and_b64 s[24:25], s[4:5], exec
	s_cselect_b32 s9, s15, s41
	s_cselect_b32 s19, s14, s40
	s_add_u32 s38, s38, 0x80080
	s_addc_u32 s39, s39, 0
	s_add_u32 s24, s40, 0x100
	s_addc_u32 s25, s41, 0
	s_mov_b32 s26, -2
	s_add_u32 s27, s38, 0xfff80080
	s_addc_u32 s30, s39, -1
	s_add_i32 s31, 0, 0x10000
	s_cmp_eq_u32 s26, 28
	s_cselect_b32 s43, s11, s30
	s_cselect_b32 s42, s18, s27
	v_add_u32_e32 v156, s31, v145
	s_cselect_b32 s41, s9, s25
	s_cselect_b32 s40, s19, s24
	s_add_i32 s27, 0, 0x14000
	ds_read_b128 v[140:143], v156
	ds_read_b128 v[148:151], v156 offset:1024
	ds_read_b128 v[152:155], v156 offset:2048
	ds_read_b128 v[164:167], v156 offset:3072
	v_add_u32_e32 v156, s27, v145
	ds_read_b128 v[168:171], v156
	ds_read_b128 v[172:175], v156 offset:1024
	ds_read_b128 v[176:179], v156 offset:2048
	ds_read_b128 v[180:183], v156 offset:3072
	v_lshl_add_u64 v[156:157], s[38:39], 0, v[136:137]
	s_add_i32 m0, s58, 0xc000
	ds_read_b128 v[184:187], v147
	ds_read_b128 v[188:191], v147 offset:1024
	ds_read_b128 v[192:195], v147 offset:2048
	ds_read_b128 v[204:207], v147 offset:3072
	ds_read_b128 v[208:211], v147 offset:4096
	ds_read_b128 v[212:215], v147 offset:5120
	ds_read_b128 v[216:219], v147 offset:6144
	ds_read_b128 v[220:223], v147 offset:7168
	global_load_lds_dwordx4 v[156:157], off
	v_lshl_add_u64 v[156:157], s[38:39], 0, v[138:139]
	s_add_i32 m0, s58, 0xe000
	s_nop 0
	global_load_lds_dwordx4 v[156:157], off
	s_waitcnt vmcnt(8)
	s_waitcnt lgkmcnt(0)
	s_barrier
	s_setprio 1
	s_waitcnt lgkmcnt(0)
	v_mfma_f32_16x16x32_bf16 v[128:131], v[140:143], v[184:187], 0
	v_mfma_f32_16x16x32_bf16 v[128:131], v[148:151], v[188:191], v[128:131]
	v_mfma_f32_16x16x32_bf16 v[124:127], v[152:155], v[184:187], 0
	v_mfma_f32_16x16x32_bf16 v[124:127], v[164:167], v[188:191], v[124:127]
	v_mfma_f32_16x16x32_bf16 v[120:123], v[140:143], v[192:195], 0
	v_mfma_f32_16x16x32_bf16 v[120:123], v[148:151], v[204:207], v[120:123]
	v_mfma_f32_16x16x32_bf16 v[112:115], v[152:155], v[192:195], 0
	v_mfma_f32_16x16x32_bf16 v[112:115], v[164:167], v[204:207], v[112:115]
	v_mfma_f32_16x16x32_bf16 v[104:107], v[140:143], v[208:211], 0
	v_mfma_f32_16x16x32_bf16 v[104:107], v[148:151], v[212:215], v[104:107]
	v_mfma_f32_16x16x32_bf16 v[96:99], v[152:155], v[208:211], 0
	v_mfma_f32_16x16x32_bf16 v[96:99], v[164:167], v[212:215], v[96:99]
	v_mfma_f32_16x16x32_bf16 v[88:91], v[140:143], v[216:219], 0
	v_mfma_f32_16x16x32_bf16 v[88:91], v[148:151], v[220:223], v[88:91]
	v_mfma_f32_16x16x32_bf16 v[80:83], v[152:155], v[216:219], 0
	v_mfma_f32_16x16x32_bf16 v[80:83], v[164:167], v[220:223], v[80:83]
	s_setprio 0
	s_setprio 1
	v_mfma_f32_16x16x32_bf16 v[116:119], v[168:171], v[184:187], 0
	v_mfma_f32_16x16x32_bf16 v[116:119], v[172:175], v[188:191], v[116:119]
	v_mfma_f32_16x16x32_bf16 v[108:111], v[176:179], v[184:187], 0
	v_mfma_f32_16x16x32_bf16 v[108:111], v[180:183], v[188:191], v[108:111]
	v_mfma_f32_16x16x32_bf16 v[100:103], v[168:171], v[192:195], 0
	v_mfma_f32_16x16x32_bf16 v[100:103], v[172:175], v[204:207], v[100:103]
	v_mfma_f32_16x16x32_bf16 v[92:95], v[176:179], v[192:195], 0
	v_mfma_f32_16x16x32_bf16 v[92:95], v[180:183], v[204:207], v[92:95]
	v_mfma_f32_16x16x32_bf16 v[84:87], v[168:171], v[208:211], 0
	v_mfma_f32_16x16x32_bf16 v[84:87], v[172:175], v[212:215], v[84:87]
	v_mfma_f32_16x16x32_bf16 v[76:79], v[176:179], v[208:211], 0
	v_mfma_f32_16x16x32_bf16 v[76:79], v[180:183], v[212:215], v[76:79]
	s_setprio 2
	s_barrier
	v_mfma_f32_16x16x32_bf16 v[72:75], v[168:171], v[216:219], 0
	v_mfma_f32_16x16x32_bf16 v[72:75], v[172:175], v[220:223], v[72:75]
	v_mfma_f32_16x16x32_bf16 v[68:71], v[176:179], v[216:219], 0
	v_mfma_f32_16x16x32_bf16 v[68:71], v[180:183], v[220:223], v[68:71]
	s_setprio 0
	s_add_i32 s30, s31, s53
	v_lshl_add_u64 v[156:157], s[40:41], 0, v[2:3]
	s_mov_b32 m0, s30
	ds_read_b128 v[184:187], v147 offset:16384
	ds_read_b128 v[188:191], v147 offset:17408
	ds_read_b128 v[192:195], v147 offset:18432
	ds_read_b128 v[204:207], v147 offset:19456
	ds_read_b128 v[208:211], v147 offset:20480
	ds_read_b128 v[212:215], v147 offset:21504
	ds_read_b128 v[216:219], v147 offset:22528
	ds_read_b128 v[220:223], v147 offset:23552
	global_load_lds_dwordx4 v[156:157], off
	s_add_i32 m0, s30, 0x2000
	s_add_u32 s30, s40, 0x80000
	v_lshl_add_u64 v[196:197], s[40:41], 0, v[0:1]
	s_addc_u32 s31, s41, 0
	s_add_i32 s27, s27, s53
	global_load_lds_dwordx4 v[196:197], off
	v_lshl_add_u64 v[224:225], s[30:31], 0, v[2:3]
	s_mov_b32 m0, s27
	v_lshl_add_u64 v[226:227], s[42:43], 0, v[132:133]
	global_load_lds_dwordx4 v[224:225], off
	v_lshl_add_u64 v[224:225], s[30:31], 0, v[0:1]
	s_add_i32 m0, s27, 0x2000
	s_nop 0
	global_load_lds_dwordx4 v[224:225], off
	v_lshl_add_u64 v[224:225], s[42:43], 0, v[134:135]
	s_mov_b32 m0, s58
	s_nop 0
	global_load_lds_dwordx4 v[224:225], off
	s_mov_b32 m0, s59
	s_nop 0
	global_load_lds_dwordx4 v[226:227], off
	s_waitcnt vmcnt(8)
	s_waitcnt lgkmcnt(0)
	s_barrier
; #define PG8_STAGE(bufoff, gbase, voff) do { _Pragma("unroll") for (int _i = 0; _i < 2; ++_i) \
;         __builtin_amdgcn_global_load_lds((const unsigned*)((const char*)(gbase) + (voff)[_i]), (LAS unsigned*)(lds + (bufoff) + ldsw + _i * 8192), 16, 0, 0); } while (0)
; #define PG8_LDA(dst, b, h) do { _Pragma("unroll") for (int m = 0; m < 4; ++m) _Pragma("unroll") for (int k = 0; k < 2; ++k) dst[m][k] = *(const LAS bf16x8*)(lds + PG8_SA(b, h) + aoff + m * 2048 + k * 1024); } while (0)
; #define PG8_LDB(dst, b, h) do { _Pragma("unroll") for (int n = 0; n < 2; ++n) _Pragma("unroll") for (int k = 0; k < 2; ++k) dst[n][k] = *(const LAS bf16x8*)(lds + PG8_SB(b, h) + boff + n * 2048 + k * 1024); } while (0)
; #define PG8_MMA(ai, bj, At, Bt) do { __builtin_amdgcn_s_setprio(1); _Pragma("unroll") for (int m = 0; m < 4; ++m) _Pragma("unroll") for (int n = 0; n < 2; ++n) _Pragma("unroll") for (int k = 0; k < 2; ++k) \
;         acc[ai][bj][m][n] = __builtin_amdgcn_mfma_f32_16x16x32_bf16(Bt[n][k], At[m][k], acc[ai][bj][m][n], 0, 0, 0); __builtin_amdgcn_s_setprio(0); } while (0)
; #define PG8_WAIT_V(n) asm volatile("s_waitcnt vmcnt(" #n ")" ::: "memory")
; #define PG8_WAIT_L(n) asm volatile("s_waitcnt lgkmcnt(" #n ")" ::: "memory")
; #define PG8_BAR __builtin_amdgcn_s_barrier()
; #define PG8_SCHED __builtin_amdgcn_sched_barrier(0)
; template <class Epi, class Sched, bool ALIGN_EPI = true>
; __device__ __forceinline__ void gemm_phase(LAS unsigned char* lds, const Gemm g, const Sched& S, const Epi& E) {
;     ...
;             PG8_WAIT_V(8); PG8_WAIT_L(0); PG8_BAR; PG8_MMA(1, 0, At, B0); PG8_MMA(1, 1, At, B1); PG8_BAR; PG8_SCHED;
;             PG8_LDB(B0, 1, 0); PG8_LDB(B1, 1, 1); PG8_SCHED; PG8_LDA(At, 1, 0); PG8_STAGE(PG8_SA(0, 1), a2 + hA, voffA);
;             PG8_WAIT_V(8); PG8_WAIT_L(0); PG8_BAR; PG8_MMA(0, 0, At, B0); PG8_MMA(0, 1, At, B1); PG8_BAR; PG8_SCHED;
	s_setprio 1
	s_waitcnt lgkmcnt(0)
	v_mfma_f32_16x16x32_bf16 v[64:67], v[140:143], v[184:187], 0
	v_mfma_f32_16x16x32_bf16 v[64:67], v[148:151], v[188:191], v[64:67]
	v_mfma_f32_16x16x32_bf16 v[60:63], v[152:155], v[184:187], 0
	v_mfma_f32_16x16x32_bf16 v[60:63], v[164:167], v[188:191], v[60:63]
	v_mfma_f32_16x16x32_bf16 v[56:59], v[140:143], v[192:195], 0
	v_mfma_f32_16x16x32_bf16 v[56:59], v[148:151], v[204:207], v[56:59]
	v_mfma_f32_16x16x32_bf16 v[48:51], v[152:155], v[192:195], 0
	v_mfma_f32_16x16x32_bf16 v[48:51], v[164:167], v[204:207], v[48:51]
	v_mfma_f32_16x16x32_bf16 v[40:43], v[140:143], v[208:211], 0
	v_mfma_f32_16x16x32_bf16 v[40:43], v[148:151], v[212:215], v[40:43]
	v_mfma_f32_16x16x32_bf16 v[32:35], v[152:155], v[208:211], 0
	v_mfma_f32_16x16x32_bf16 v[32:35], v[164:167], v[212:215], v[32:35]
	v_mfma_f32_16x16x32_bf16 v[24:27], v[140:143], v[216:219], 0
	v_mfma_f32_16x16x32_bf16 v[24:27], v[148:151], v[220:223], v[24:27]
	v_mfma_f32_16x16x32_bf16 v[16:19], v[152:155], v[216:219], 0
	v_mfma_f32_16x16x32_bf16 v[16:19], v[164:167], v[220:223], v[16:19]
	s_setprio 0
	s_setprio 1
	v_mfma_f32_16x16x32_bf16 v[52:55], v[168:171], v[184:187], 0
	v_mfma_f32_16x16x32_bf16 v[52:55], v[172:175], v[188:191], v[52:55]
	v_mfma_f32_16x16x32_bf16 v[44:47], v[176:179], v[184:187], 0
	v_mfma_f32_16x16x32_bf16 v[44:47], v[180:183], v[188:191], v[44:47]
	v_mfma_f32_16x16x32_bf16 v[36:39], v[168:171], v[192:195], 0
	v_mfma_f32_16x16x32_bf16 v[36:39], v[172:175], v[204:207], v[36:39]
	v_mfma_f32_16x16x32_bf16 v[28:31], v[176:179], v[192:195], 0
	v_mfma_f32_16x16x32_bf16 v[28:31], v[180:183], v[204:207], v[28:31]
	v_mfma_f32_16x16x32_bf16 v[20:23], v[168:171], v[208:211], 0
	v_mfma_f32_16x16x32_bf16 v[20:23], v[172:175], v[212:215], v[20:23]
	v_mfma_f32_16x16x32_bf16 v[12:15], v[176:179], v[208:211], 0
	v_mfma_f32_16x16x32_bf16 v[12:15], v[180:183], v[212:215], v[12:15]
	s_setprio 2
	s_barrier
	v_mfma_f32_16x16x32_bf16 v[8:11], v[168:171], v[216:219], 0
	v_mfma_f32_16x16x32_bf16 v[8:11], v[172:175], v[220:223], v[8:11]
	v_mfma_f32_16x16x32_bf16 v[4:7], v[176:179], v[216:219], 0
	v_mfma_f32_16x16x32_bf16 v[4:7], v[180:183], v[220:223], v[4:7]
	s_setprio 0
	s_add_i32 s27, 0, 0x18000
	v_add_u32_e32 v158, s27, v145
	s_add_i32 s65, 0, 0x1c000
	ds_read_b128 v[140:143], v158
	ds_read_b128 v[148:151], v158 offset:1024
	ds_read_b128 v[152:155], v158 offset:2048
	ds_read_b128 v[164:167], v158 offset:3072
	v_add_u32_e32 v158, s65, v145
	ds_read_b128 v[168:171], v158
	ds_read_b128 v[172:175], v158 offset:1024
	ds_read_b128 v[176:179], v158 offset:2048
	ds_read_b128 v[180:183], v158 offset:3072
	s_add_u32 s30, s42, 0x80000
	s_addc_u32 s31, s43, 0
	s_mov_b32 m0, s60
	v_lshl_add_u64 v[228:229], s[30:31], 0, v[134:135]
	ds_read_b128 v[184:187], v147 offset:32768
	ds_read_b128 v[188:191], v147 offset:33792
	ds_read_b128 v[192:195], v147 offset:34816
	ds_read_b128 v[204:207], v147 offset:35840
	ds_read_b128 v[208:211], v147 offset:36864
	ds_read_b128 v[212:215], v147 offset:37888
	ds_read_b128 v[216:219], v147 offset:38912
	ds_read_b128 v[220:223], v147 offset:39936
	global_load_lds_dwordx4 v[228:229], off
	v_lshl_add_u64 v[228:229], s[30:31], 0, v[132:133]
	s_mov_b32 m0, s61
	s_nop 0
	global_load_lds_dwordx4 v[228:229], off
	s_waitcnt vmcnt(8)
	s_waitcnt lgkmcnt(0)
	s_barrier
	s_setprio 1
	s_waitcnt lgkmcnt(0)
	v_mfma_f32_16x16x32_bf16 v[128:131], v[140:143], v[184:187], v[128:131]
	v_mfma_f32_16x16x32_bf16 v[128:131], v[148:151], v[188:191], v[128:131]
	v_mfma_f32_16x16x32_bf16 v[124:127], v[152:155], v[184:187], v[124:127]
	v_mfma_f32_16x16x32_bf16 v[124:127], v[164:167], v[188:191], v[124:127]
	v_mfma_f32_16x16x32_bf16 v[120:123], v[140:143], v[192:195], v[120:123]
	v_mfma_f32_16x16x32_bf16 v[120:123], v[148:151], v[204:207], v[120:123]
	v_mfma_f32_16x16x32_bf16 v[112:115], v[152:155], v[192:195], v[112:115]
	v_mfma_f32_16x16x32_bf16 v[112:115], v[164:167], v[204:207], v[112:115]
	v_mfma_f32_16x16x32_bf16 v[104:107], v[140:143], v[208:211], v[104:107]
	v_mfma_f32_16x16x32_bf16 v[104:107], v[148:151], v[212:215], v[104:107]
	v_mfma_f32_16x16x32_bf16 v[96:99], v[152:155], v[208:211], v[96:99]
	v_mfma_f32_16x16x32_bf16 v[96:99], v[164:167], v[212:215], v[96:99]
	v_mfma_f32_16x16x32_bf16 v[88:91], v[140:143], v[216:219], v[88:91]
	v_mfma_f32_16x16x32_bf16 v[88:91], v[148:151], v[220:223], v[88:91]
	v_mfma_f32_16x16x32_bf16 v[80:83], v[152:155], v[216:219], v[80:83]
	v_mfma_f32_16x16x32_bf16 v[80:83], v[164:167], v[220:223], v[80:83]
	s_setprio 0
	s_setprio 1
	v_mfma_f32_16x16x32_bf16 v[116:119], v[168:171], v[184:187], v[116:119]
	v_mfma_f32_16x16x32_bf16 v[116:119], v[172:175], v[188:191], v[116:119]
	v_mfma_f32_16x16x32_bf16 v[108:111], v[176:179], v[184:187], v[108:111]
	v_mfma_f32_16x16x32_bf16 v[108:111], v[180:183], v[188:191], v[108:111]
	v_mfma_f32_16x16x32_bf16 v[100:103], v[168:171], v[192:195], v[100:103]
	v_mfma_f32_16x16x32_bf16 v[100:103], v[172:175], v[204:207], v[100:103]
	v_mfma_f32_16x16x32_bf16 v[92:95], v[176:179], v[192:195], v[92:95]
	v_mfma_f32_16x16x32_bf16 v[92:95], v[180:183], v[204:207], v[92:95]
	v_mfma_f32_16x16x32_bf16 v[84:87], v[168:171], v[208:211], v[84:87]
	v_mfma_f32_16x16x32_bf16 v[84:87], v[172:175], v[212:215], v[84:87]
	v_mfma_f32_16x16x32_bf16 v[76:79], v[176:179], v[208:211], v[76:79]
	v_mfma_f32_16x16x32_bf16 v[76:79], v[180:183], v[212:215], v[76:79]
	s_setprio 2
	s_barrier
; #define PG8_STAGE(bufoff, gbase, voff) do { _Pragma("unroll") for (int _i = 0; _i < 2; ++_i) \
;         __builtin_amdgcn_global_load_lds((const unsigned*)((const char*)(gbase) + (voff)[_i]), (LAS unsigned*)(lds + (bufoff) + ldsw + _i * 8192), 16, 0, 0); } while (0)
; #define PG8_LDA(dst, b, h) do { _Pragma("unroll") for (int m = 0; m < 4; ++m) _Pragma("unroll") for (int k = 0; k < 2; ++k) dst[m][k] = *(const LAS bf16x8*)(lds + PG8_SA(b, h) + aoff + m * 2048 + k * 1024); } while (0)
; #define PG8_MMA(ai, bj, At, Bt) do { __builtin_amdgcn_s_setprio(1); _Pragma("unroll") for (int m = 0; m < 4; ++m) _Pragma("unroll") for (int n = 0; n < 2; ++n) _Pragma("unroll") for (int k = 0; k < 2; ++k) \
;         acc[ai][bj][m][n] = __builtin_amdgcn_mfma_f32_16x16x32_bf16(Bt[n][k], At[m][k], acc[ai][bj][m][n], 0, 0, 0); __builtin_amdgcn_s_setprio(0); } while (0)
; #define PG8_WAIT_V(n) asm volatile("s_waitcnt vmcnt(" #n ")" ::: "memory")
; #define PG8_WAIT_L(n) asm volatile("s_waitcnt lgkmcnt(" #n ")" ::: "memory")
; #define PG8_BAR __builtin_amdgcn_s_barrier()
; #define PG8_SCHED __builtin_amdgcn_sched_barrier(0)
; template <class Epi, class Sched, bool ALIGN_EPI = true>
; __device__ __forceinline__ void gemm_phase(LAS unsigned char* lds, const Gemm g, const Sched& S, const Epi& E) {
;     ...
;             PG8_WAIT_V(8); PG8_WAIT_L(0); PG8_BAR; PG8_MMA(0, 0, At, B0); PG8_MMA(0, 1, At, B1); PG8_BAR; PG8_SCHED;
;             PG8_LDA(At, 1, 1); PG8_STAGE(PG8_SB(1, 0), b3, voffB); PG8_STAGE(PG8_SB(1, 1), b3 + hB, voffB); PG8_STAGE(PG8_SA(1, 0), a3, voffA);
;             PG8_WAIT_V(8); PG8_WAIT_L(0); PG8_BAR; PG8_MMA(1, 0, At, B0); PG8_MMA(1, 1, At, B1); PG8_BAR; PG8_SCHED;
;         }
	v_mfma_f32_16x16x32_bf16 v[72:75], v[168:171], v[216:219], v[72:75]
	v_mfma_f32_16x16x32_bf16 v[72:75], v[172:175], v[220:223], v[72:75]
	v_mfma_f32_16x16x32_bf16 v[68:71], v[176:179], v[216:219], v[68:71]
	v_mfma_f32_16x16x32_bf16 v[68:71], v[180:183], v[220:223], v[68:71]
	s_setprio 0
	s_add_i32 s27, s27, s53
	v_lshl_add_u64 v[156:157], v[156:157], 0, s[86:87]
	s_mov_b32 m0, s27
	ds_read_b128 v[184:187], v147 offset:49152
	ds_read_b128 v[188:191], v147 offset:50176
	ds_read_b128 v[192:195], v147 offset:51200
	ds_read_b128 v[204:207], v147 offset:52224
	ds_read_b128 v[208:211], v147 offset:53248
	ds_read_b128 v[212:215], v147 offset:54272
	ds_read_b128 v[216:219], v147 offset:55296
	ds_read_b128 v[220:223], v147 offset:56320
	global_load_lds_dwordx4 v[156:157], off
	s_add_i32 m0, s27, 0x2000
	s_add_u32 s30, s40, 0x80080
	v_lshl_add_u64 v[156:157], v[196:197], 0, s[86:87]
	s_addc_u32 s31, s41, 0
	s_add_i32 s27, s65, s53
	global_load_lds_dwordx4 v[156:157], off
	v_lshl_add_u64 v[156:157], s[30:31], 0, v[2:3]
	s_mov_b32 m0, s27
	s_nop 0
	global_load_lds_dwordx4 v[156:157], off
	v_lshl_add_u64 v[156:157], s[30:31], 0, v[0:1]
	s_add_i32 m0, s27, 0x2000
	s_nop 0
	global_load_lds_dwordx4 v[156:157], off
	v_lshl_add_u64 v[156:157], v[224:225], 0, s[86:87]
	s_mov_b32 m0, s62
	s_nop 0
	global_load_lds_dwordx4 v[156:157], off
	v_lshl_add_u64 v[156:157], v[226:227], 0, s[86:87]
	s_mov_b32 m0, s63
	s_nop 0
	global_load_lds_dwordx4 v[156:157], off
	s_waitcnt vmcnt(8)
	s_waitcnt lgkmcnt(0)
	s_barrier
	s_setprio 1
	s_waitcnt lgkmcnt(0)
	v_mfma_f32_16x16x32_bf16 v[64:67], v[140:143], v[184:187], v[64:67]
	v_mfma_f32_16x16x32_bf16 v[64:67], v[148:151], v[188:191], v[64:67]
	v_mfma_f32_16x16x32_bf16 v[60:63], v[152:155], v[184:187], v[60:63]
	v_mfma_f32_16x16x32_bf16 v[60:63], v[164:167], v[188:191], v[60:63]
	v_mfma_f32_16x16x32_bf16 v[56:59], v[140:143], v[192:195], v[56:59]
	v_mfma_f32_16x16x32_bf16 v[56:59], v[148:151], v[204:207], v[56:59]
	v_mfma_f32_16x16x32_bf16 v[48:51], v[152:155], v[192:195], v[48:51]
	v_mfma_f32_16x16x32_bf16 v[48:51], v[164:167], v[204:207], v[48:51]
	v_mfma_f32_16x16x32_bf16 v[40:43], v[140:143], v[208:211], v[40:43]
	v_mfma_f32_16x16x32_bf16 v[40:43], v[148:151], v[212:215], v[40:43]
	v_mfma_f32_16x16x32_bf16 v[32:35], v[152:155], v[208:211], v[32:35]
	v_mfma_f32_16x16x32_bf16 v[32:35], v[164:167], v[212:215], v[32:35]
	v_mfma_f32_16x16x32_bf16 v[24:27], v[140:143], v[216:219], v[24:27]
	v_mfma_f32_16x16x32_bf16 v[24:27], v[148:151], v[220:223], v[24:27]
	v_mfma_f32_16x16x32_bf16 v[16:19], v[152:155], v[216:219], v[16:19]
	v_mfma_f32_16x16x32_bf16 v[16:19], v[164:167], v[220:223], v[16:19]
	s_setprio 0
	s_setprio 1
	v_mfma_f32_16x16x32_bf16 v[52:55], v[168:171], v[184:187], v[52:55]
	v_mfma_f32_16x16x32_bf16 v[52:55], v[172:175], v[188:191], v[52:55]
	v_mfma_f32_16x16x32_bf16 v[44:47], v[176:179], v[184:187], v[44:47]
	v_mfma_f32_16x16x32_bf16 v[44:47], v[180:183], v[188:191], v[44:47]
	v_mfma_f32_16x16x32_bf16 v[36:39], v[168:171], v[192:195], v[36:39]
	v_mfma_f32_16x16x32_bf16 v[36:39], v[172:175], v[204:207], v[36:39]
	v_mfma_f32_16x16x32_bf16 v[28:31], v[176:179], v[192:195], v[28:31]
	v_mfma_f32_16x16x32_bf16 v[28:31], v[180:183], v[204:207], v[28:31]
	v_mfma_f32_16x16x32_bf16 v[20:23], v[168:171], v[208:211], v[20:23]
	v_mfma_f32_16x16x32_bf16 v[20:23], v[172:175], v[212:215], v[20:23]
	v_mfma_f32_16x16x32_bf16 v[12:15], v[176:179], v[208:211], v[12:15]
	v_mfma_f32_16x16x32_bf16 v[12:15], v[180:183], v[212:215], v[12:15]
	s_setprio 2
	s_barrier
	v_mfma_f32_16x16x32_bf16 v[8:11], v[168:171], v[216:219], v[8:11]
	v_mfma_f32_16x16x32_bf16 v[8:11], v[172:175], v[220:223], v[8:11]
	v_mfma_f32_16x16x32_bf16 v[4:7], v[176:179], v[216:219], v[4:7]
	v_mfma_f32_16x16x32_bf16 v[4:7], v[180:183], v[220:223], v[4:7]
	s_setprio 0
	s_add_i32 s26, s26, 2
	s_add_u32 s38, s38, 0x100
	s_addc_u32 s39, s39, 0
	s_add_u32 s24, s24, 0x100
	s_addc_u32 s25, s25, 0
	s_cmp_gt_u32 s26, 29
	s_cbranch_scc1 .Lpeel_exit_218

; #define PG8_BAR __builtin_amdgcn_s_barrier()
; template <class Epi, class Sched, bool ALIGN_EPI = true>
; __device__ __forceinline__ void gemm_phase(LAS unsigned char* lds, const Gemm g, const Sched& S, const Epi& E) {
;     ...
;         if constexpr (ALIGN_EPI) { if (wr == 0) PG8_BAR; }
.Lpeel_exit_218:
	s_and_b64 vcc, exec, s[6:7]
	s_cbranch_vccz .LBB0_221
	s_barrier

;     __device__ bool next(int i, Unit& u) const { if (i >= 2) return false; const int x = c & 7, j = c >> 3; u.pm = 32 * i + 4 * x + (j & 3); u.pn = j >> 2; return true; }
; #define PG8_STAGE(bufoff, gbase, voff) do { _Pragma("unroll") for (int _i = 0; _i < 2; ++_i) \
;         __builtin_amdgcn_global_load_lds((const unsigned*)((const char*)(gbase) + (voff)[_i]), (LAS unsigned*)(lds + (bufoff) + ldsw + _i * 8192), 16, 0, 0); } while (0)
; #define PG8_LDA(dst, b, h) do { _Pragma("unroll") for (int m = 0; m < 4; ++m) _Pragma("unroll") for (int k = 0; k < 2; ++k) dst[m][k] = *(const LAS bf16x8*)(lds + PG8_SA(b, h) + aoff + m * 2048 + k * 1024); } while (0)
; #define PG8_LDB(dst, b, h) do { _Pragma("unroll") for (int n = 0; n < 2; ++n) _Pragma("unroll") for (int k = 0; k < 2; ++k) dst[n][k] = *(const LAS bf16x8*)(lds + PG8_SB(b, h) + boff + n * 2048 + k * 1024); } while (0)
; #define PG8_WAIT_V(n) asm volatile("s_waitcnt vmcnt(" #n ")" ::: "memory")
; #define PG8_WAIT_L(n) asm volatile("s_waitcnt lgkmcnt(" #n ")" ::: "memory")
; #define PG8_BAR __builtin_amdgcn_s_barrier()
; template <class Epi, class Sched, bool ALIGN_EPI = true>
; __device__ __forceinline__ void gemm_phase(LAS unsigned char* lds, const Gemm g, const Sched& S, const Epi& E) {
;     ...
;         const bool has_next = S.next(ui + 1, nxt);
;         const char* nA = has_next ? (const char*)g.A + ((size_t)nxt.pm * BM * g.lda + (size_t)nxt.pn * g.a_pn_off) * 2 : cA; const char* nB = has_next ? (const char*)g.Bt + (size_t)nxt.pn * BM * g.ldb * 2 : cB;
;         for (int t = 0; t < nt; t += 2) {
;             const bool last = (t == nt - 2);
;             const char* a1 = cA + (size_t)(t + 1) * kstep;
;             const char* a2 = last ? nA : cA + (size_t)(t + 2) * kstep; const char* b2 = last ? nB : cB + (size_t)(t + 2) * kstep;
;             const char* a3 = a2 + kstep; const char* b3 = b2 + kstep;
;             PG8_LDB(B0, 0, 0); PG8_LDB(B1, 0, 1); PG8_SCHED; PG8_LDA(At, 0, 0); PG8_STAGE(PG8_SA(1, 1), a1 + hA, voffA);
;             PG8_WAIT_V(8); PG8_WAIT_L(0); PG8_BAR; PG8_MMA(0, 0, At, B0); PG8_MMA(0, 1, At, B1); PG8_BAR; PG8_SCHED;
;             PG8_LDA(At, 0, 1); PG8_STAGE(PG8_SB(0, 0), b2, voffB); PG8_STAGE(PG8_SB(0, 1), b2 + hB, voffB); PG8_STAGE(PG8_SA(0, 0), a2, voffA);
;             PG8_WAIT_V(8); PG8_WAIT_L(0); PG8_BAR; PG8_MMA(1, 0, At, B0); PG8_MMA(1, 1, At, B1); PG8_BAR; PG8_SCHED;
.LBB0_666:
	s_mov_b32 s82, s81
	s_or_b32 s81, s17, s68
	s_mov_b64 s[10:11], s[12:13]
	s_lshl_b32 s12, s81, 20
	s_add_u32 s12, s28, s12
	s_addc_u32 s13, s29, 0
	s_and_b64 s[16:17], s[38:39], exec
	s_cselect_b32 s16, s13, s11
	s_cselect_b32 s17, s12, s10
	s_add_u32 s18, s10, 0x100
	s_addc_u32 s19, s11, 0
	s_add_u32 s10, s10, 0x80080
	s_addc_u32 s11, s11, 0
	v_lshl_add_u64 v[132:133], s[10:11], 0, v[166:167]
	v_lshl_add_u64 v[134:135], s[10:11], 0, v[168:169]
	s_mov_b32 s24, -2
	s_mov_b64 s[10:11], 0
	s_add_u32 vcc_lo, s10, 0x100
	s_addc_u32 vcc_hi, s11, 0
	s_add_u32 s25, s18, s10
	s_addc_u32 s26, s19, s11
	s_add_i32 s27, 0, 0x10000
	s_cmp_eq_u32 s24, 28
	s_cselect_b32 s65, s16, s26
	s_cselect_b32 s26, 0, vcc_lo
	s_cselect_b32 s64, s17, s25
	s_cselect_b32 s25, 0, vcc_hi
	s_add_u32 s62, s14, s26
	v_add_u32_e32 v160, s27, v186
	s_addc_u32 s63, s15, s25
	s_add_i32 s25, 0, 0x14000
	ds_read_b128 v[136:139], v160
	ds_read_b128 v[140:143], v160 offset:1024
	ds_read_b128 v[144:147], v160 offset:2048
	ds_read_b128 v[170:173], v160 offset:3072
	v_add_u32_e32 v160, s25, v186
	ds_read_b128 v[174:177], v160
	ds_read_b128 v[178:181], v160 offset:1024
	ds_read_b128 v[182:185], v160 offset:2048
	ds_read_b128 v[208:211], v160 offset:3072
	v_lshl_add_u64 v[244:245], v[132:133], 0, s[10:11]
	s_add_i32 m0, s53, 0xc000
	ds_read_b128 v[212:215], v197
	ds_read_b128 v[216:219], v197 offset:1024
	ds_read_b128 v[220:223], v197 offset:2048
	ds_read_b128 v[224:227], v197 offset:3072
	ds_read_b128 v[228:231], v197 offset:4096
	ds_read_b128 v[232:235], v197 offset:5120
	ds_read_b128 v[236:239], v197 offset:6144
	ds_read_b128 v[240:243], v197 offset:7168
	global_load_lds_dwordx4 v[244:245], off
	v_lshl_add_u64 v[244:245], v[134:135], 0, s[10:11]
	s_add_i32 m0, s53, 0xe000
	s_nop 0
	global_load_lds_dwordx4 v[244:245], off
	s_waitcnt vmcnt(8)
	s_waitcnt lgkmcnt(0)
	s_barrier
	s_setprio 1
	s_waitcnt lgkmcnt(0)
	v_mfma_f32_16x16x32_bf16 v[36:39], v[136:139], v[212:215], 0
	v_mfma_f32_16x16x32_bf16 v[36:39], v[140:143], v[216:219], v[36:39]
	v_mfma_f32_16x16x32_bf16 v[40:43], v[144:147], v[212:215], 0
	v_mfma_f32_16x16x32_bf16 v[40:43], v[170:173], v[216:219], v[40:43]
	v_mfma_f32_16x16x32_bf16 v[68:71], v[136:139], v[220:223], 0
	v_mfma_f32_16x16x32_bf16 v[68:71], v[140:143], v[224:227], v[68:71]
	v_mfma_f32_16x16x32_bf16 v[72:75], v[144:147], v[220:223], 0
	v_mfma_f32_16x16x32_bf16 v[72:75], v[170:173], v[224:227], v[72:75]
	v_mfma_f32_16x16x32_bf16 v[100:103], v[136:139], v[228:231], 0
	v_mfma_f32_16x16x32_bf16 v[100:103], v[140:143], v[232:235], v[100:103]
	v_mfma_f32_16x16x32_bf16 v[104:107], v[144:147], v[228:231], 0
	v_mfma_f32_16x16x32_bf16 v[104:107], v[170:173], v[232:235], v[104:107]
	v_mfma_f32_16x16x32_bf16 v[128:131], v[136:139], v[236:239], 0
	v_mfma_f32_16x16x32_bf16 v[128:131], v[140:143], v[240:243], v[128:131]
	v_mfma_f32_16x16x32_bf16 v[124:127], v[144:147], v[236:239], 0
	v_mfma_f32_16x16x32_bf16 v[124:127], v[170:173], v[240:243], v[124:127]
	s_setprio 0
	s_setprio 1
	v_mfma_f32_16x16x32_bf16 v[8:11], v[174:177], v[212:215], 0
	v_mfma_f32_16x16x32_bf16 v[8:11], v[178:181], v[216:219], v[8:11]
	v_mfma_f32_16x16x32_bf16 v[4:7], v[182:185], v[212:215], 0
	v_mfma_f32_16x16x32_bf16 v[4:7], v[208:211], v[216:219], v[4:7]
	v_mfma_f32_16x16x32_bf16 v[32:35], v[174:177], v[220:223], 0
	v_mfma_f32_16x16x32_bf16 v[32:35], v[178:181], v[224:227], v[32:35]
	v_mfma_f32_16x16x32_bf16 v[28:31], v[182:185], v[220:223], 0
	v_mfma_f32_16x16x32_bf16 v[28:31], v[208:211], v[224:227], v[28:31]
	v_mfma_f32_16x16x32_bf16 v[56:59], v[174:177], v[228:231], 0
	v_mfma_f32_16x16x32_bf16 v[56:59], v[178:181], v[232:235], v[56:59]
	v_mfma_f32_16x16x32_bf16 v[52:55], v[182:185], v[228:231], 0
	v_mfma_f32_16x16x32_bf16 v[52:55], v[208:211], v[232:235], v[52:55]
	s_setprio 2
	s_barrier
	v_mfma_f32_16x16x32_bf16 v[80:83], v[174:177], v[236:239], 0
	v_mfma_f32_16x16x32_bf16 v[80:83], v[178:181], v[240:243], v[80:83]
	v_mfma_f32_16x16x32_bf16 v[76:79], v[182:185], v[236:239], 0
	v_mfma_f32_16x16x32_bf16 v[76:79], v[208:211], v[240:243], v[76:79]
	s_setprio 0
	s_add_i32 s10, s27, s67
	v_lshl_add_u64 v[244:245], s[62:63], 0, v[2:3]
	s_mov_b32 m0, s10
	ds_read_b128 v[212:215], v197 offset:16384
	ds_read_b128 v[216:219], v197 offset:17408
	ds_read_b128 v[220:223], v197 offset:18432
	ds_read_b128 v[224:227], v197 offset:19456
	ds_read_b128 v[228:231], v197 offset:20480
	ds_read_b128 v[232:235], v197 offset:21504
	ds_read_b128 v[236:239], v197 offset:22528
	ds_read_b128 v[240:243], v197 offset:23552
	global_load_lds_dwordx4 v[244:245], off
	s_add_i32 m0, s10, 0x2000
	s_add_u32 s10, s62, 0x80000
	v_lshl_add_u64 v[246:247], s[62:63], 0, v[150:151]
	s_addc_u32 s11, s63, 0
	s_add_i32 s25, s25, s67
	global_load_lds_dwordx4 v[246:247], off
	v_lshl_add_u64 v[248:249], s[10:11], 0, v[2:3]
	s_mov_b32 m0, s25
	v_lshl_add_u64 v[160:161], s[64:65], 0, v[148:149]
	global_load_lds_dwordx4 v[248:249], off
	v_lshl_add_u64 v[248:249], s[10:11], 0, v[150:151]
	s_add_i32 m0, s25, 0x2000
	s_nop 0
	global_load_lds_dwordx4 v[248:249], off
	v_lshl_add_u64 v[248:249], s[64:65], 0, v[0:1]
	s_mov_b32 m0, s53
	s_nop 0
	global_load_lds_dwordx4 v[248:249], off
	s_mov_b32 m0, s66
	s_nop 0
	global_load_lds_dwordx4 v[160:161], off
	s_waitcnt vmcnt(8)
	s_waitcnt lgkmcnt(0)
	s_barrier
; #define PG8_STAGE(bufoff, gbase, voff) do { _Pragma("unroll") for (int _i = 0; _i < 2; ++_i) \
;         __builtin_amdgcn_global_load_lds((const unsigned*)((const char*)(gbase) + (voff)[_i]), (LAS unsigned*)(lds + (bufoff) + ldsw + _i * 8192), 16, 0, 0); } while (0)
; #define PG8_LDA(dst, b, h) do { _Pragma("unroll") for (int m = 0; m < 4; ++m) _Pragma("unroll") for (int k = 0; k < 2; ++k) dst[m][k] = *(const LAS bf16x8*)(lds + PG8_SA(b, h) + aoff + m * 2048 + k * 1024); } while (0)
; #define PG8_LDB(dst, b, h) do { _Pragma("unroll") for (int n = 0; n < 2; ++n) _Pragma("unroll") for (int k = 0; k < 2; ++k) dst[n][k] = *(const LAS bf16x8*)(lds + PG8_SB(b, h) + boff + n * 2048 + k * 1024); } while (0)
; #define PG8_MMA(ai, bj, At, Bt) do { __builtin_amdgcn_s_setprio(1); _Pragma("unroll") for (int m = 0; m < 4; ++m) _Pragma("unroll") for (int n = 0; n < 2; ++n) _Pragma("unroll") for (int k = 0; k < 2; ++k) \
;         acc[ai][bj][m][n] = __builtin_amdgcn_mfma_f32_16x16x32_bf16(Bt[n][k], At[m][k], acc[ai][bj][m][n], 0, 0, 0); __builtin_amdgcn_s_setprio(0); } while (0)
; #define PG8_WAIT_V(n) asm volatile("s_waitcnt vmcnt(" #n ")" ::: "memory")
; #define PG8_WAIT_L(n) asm volatile("s_waitcnt lgkmcnt(" #n ")" ::: "memory")
; #define PG8_BAR __builtin_amdgcn_s_barrier()
; #define PG8_SCHED __builtin_amdgcn_sched_barrier(0)
; template <class Epi, class Sched, bool ALIGN_EPI = true>
; __device__ __forceinline__ void gemm_phase(LAS unsigned char* lds, const Gemm g, const Sched& S, const Epi& E) {
;     ...
;             PG8_WAIT_V(8); PG8_WAIT_L(0); PG8_BAR; PG8_MMA(1, 0, At, B0); PG8_MMA(1, 1, At, B1); PG8_BAR; PG8_SCHED;
;             PG8_LDB(B0, 1, 0); PG8_LDB(B1, 1, 1); PG8_SCHED; PG8_LDA(At, 1, 0); PG8_STAGE(PG8_SA(0, 1), a2 + hA, voffA);
;             PG8_WAIT_V(8); PG8_WAIT_L(0); PG8_BAR; PG8_MMA(0, 0, At, B0); PG8_MMA(0, 1, At, B1); PG8_BAR; PG8_SCHED;
	s_setprio 1
	s_waitcnt lgkmcnt(0)
	v_mfma_f32_16x16x32_bf16 v[120:123], v[136:139], v[212:215], 0
	v_mfma_f32_16x16x32_bf16 v[120:123], v[140:143], v[216:219], v[120:123]
	v_mfma_f32_16x16x32_bf16 v[116:119], v[144:147], v[212:215], 0
	v_mfma_f32_16x16x32_bf16 v[116:119], v[170:173], v[216:219], v[116:119]
	v_mfma_f32_16x16x32_bf16 v[96:99], v[136:139], v[220:223], 0
	v_mfma_f32_16x16x32_bf16 v[96:99], v[140:143], v[224:227], v[96:99]
	v_mfma_f32_16x16x32_bf16 v[92:95], v[144:147], v[220:223], 0
	v_mfma_f32_16x16x32_bf16 v[92:95], v[170:173], v[224:227], v[92:95]
	v_mfma_f32_16x16x32_bf16 v[64:67], v[136:139], v[228:231], 0
	v_mfma_f32_16x16x32_bf16 v[64:67], v[140:143], v[232:235], v[64:67]
	v_mfma_f32_16x16x32_bf16 v[60:63], v[144:147], v[228:231], 0
	v_mfma_f32_16x16x32_bf16 v[60:63], v[170:173], v[232:235], v[60:63]
	v_mfma_f32_16x16x32_bf16 v[24:27], v[136:139], v[236:239], 0
	v_mfma_f32_16x16x32_bf16 v[24:27], v[140:143], v[240:243], v[24:27]
	v_mfma_f32_16x16x32_bf16 v[20:23], v[144:147], v[236:239], 0
	v_mfma_f32_16x16x32_bf16 v[20:23], v[170:173], v[240:243], v[20:23]
	s_setprio 0
	s_setprio 1
	v_mfma_f32_16x16x32_bf16 v[112:115], v[174:177], v[212:215], 0
	v_mfma_f32_16x16x32_bf16 v[112:115], v[178:181], v[216:219], v[112:115]
	v_mfma_f32_16x16x32_bf16 v[108:111], v[182:185], v[212:215], 0
	v_mfma_f32_16x16x32_bf16 v[108:111], v[208:211], v[216:219], v[108:111]
	v_mfma_f32_16x16x32_bf16 v[88:91], v[174:177], v[220:223], 0
	v_mfma_f32_16x16x32_bf16 v[88:91], v[178:181], v[224:227], v[88:91]
	v_mfma_f32_16x16x32_bf16 v[84:87], v[182:185], v[220:223], 0
	v_mfma_f32_16x16x32_bf16 v[84:87], v[208:211], v[224:227], v[84:87]
	v_mfma_f32_16x16x32_bf16 v[48:51], v[174:177], v[228:231], 0
	v_mfma_f32_16x16x32_bf16 v[48:51], v[178:181], v[232:235], v[48:51]
	v_mfma_f32_16x16x32_bf16 v[44:47], v[182:185], v[228:231], 0
	v_mfma_f32_16x16x32_bf16 v[44:47], v[208:211], v[232:235], v[44:47]
	s_setprio 2
	s_barrier
	v_mfma_f32_16x16x32_bf16 v[16:19], v[174:177], v[236:239], 0
	v_mfma_f32_16x16x32_bf16 v[16:19], v[178:181], v[240:243], v[16:19]
	v_mfma_f32_16x16x32_bf16 v[12:15], v[182:185], v[236:239], 0
	v_mfma_f32_16x16x32_bf16 v[12:15], v[208:211], v[240:243], v[12:15]
	s_setprio 0
	s_add_i32 s25, 0, 0x18000
	v_add_u32_e32 v162, s25, v186
	s_add_i32 s26, 0, 0x1c000
	ds_read_b128 v[136:139], v162
	ds_read_b128 v[140:143], v162 offset:1024
	ds_read_b128 v[144:147], v162 offset:2048
	ds_read_b128 v[170:173], v162 offset:3072
	v_add_u32_e32 v162, s26, v186
	ds_read_b128 v[174:177], v162
	ds_read_b128 v[178:181], v162 offset:1024
	ds_read_b128 v[182:185], v162 offset:2048
	ds_read_b128 v[208:211], v162 offset:3072
	s_add_u32 s10, s64, 0x80000
	s_addc_u32 s11, s65, 0
	s_mov_b32 m0, s75
	v_lshl_add_u64 v[162:163], s[10:11], 0, v[0:1]
	ds_read_b128 v[212:215], v197 offset:32768
	ds_read_b128 v[216:219], v197 offset:33792
	ds_read_b128 v[220:223], v197 offset:34816
	ds_read_b128 v[224:227], v197 offset:35840
	ds_read_b128 v[228:231], v197 offset:36864
	ds_read_b128 v[232:235], v197 offset:37888
	ds_read_b128 v[236:239], v197 offset:38912
	ds_read_b128 v[240:243], v197 offset:39936
	global_load_lds_dwordx4 v[162:163], off
	v_lshl_add_u64 v[162:163], s[10:11], 0, v[148:149]
	s_mov_b32 m0, s76
	s_nop 0
	global_load_lds_dwordx4 v[162:163], off
	s_waitcnt vmcnt(8)
	s_waitcnt lgkmcnt(0)
	s_barrier
	s_setprio 1
	s_waitcnt lgkmcnt(0)
	v_mfma_f32_16x16x32_bf16 v[36:39], v[136:139], v[212:215], v[36:39]
	v_mfma_f32_16x16x32_bf16 v[36:39], v[140:143], v[216:219], v[36:39]
	v_mfma_f32_16x16x32_bf16 v[40:43], v[144:147], v[212:215], v[40:43]
	v_mfma_f32_16x16x32_bf16 v[40:43], v[170:173], v[216:219], v[40:43]
	v_mfma_f32_16x16x32_bf16 v[68:71], v[136:139], v[220:223], v[68:71]
	v_mfma_f32_16x16x32_bf16 v[68:71], v[140:143], v[224:227], v[68:71]
	v_mfma_f32_16x16x32_bf16 v[72:75], v[144:147], v[220:223], v[72:75]
	v_mfma_f32_16x16x32_bf16 v[72:75], v[170:173], v[224:227], v[72:75]
	v_mfma_f32_16x16x32_bf16 v[100:103], v[136:139], v[228:231], v[100:103]
	v_mfma_f32_16x16x32_bf16 v[100:103], v[140:143], v[232:235], v[100:103]
	v_mfma_f32_16x16x32_bf16 v[104:107], v[144:147], v[228:231], v[104:107]
	v_mfma_f32_16x16x32_bf16 v[104:107], v[170:173], v[232:235], v[104:107]
	v_mfma_f32_16x16x32_bf16 v[128:131], v[136:139], v[236:239], v[128:131]
	v_mfma_f32_16x16x32_bf16 v[128:131], v[140:143], v[240:243], v[128:131]
	v_mfma_f32_16x16x32_bf16 v[124:127], v[144:147], v[236:239], v[124:127]
	v_mfma_f32_16x16x32_bf16 v[124:127], v[170:173], v[240:243], v[124:127]
	s_setprio 0
	s_setprio 1
	v_mfma_f32_16x16x32_bf16 v[8:11], v[174:177], v[212:215], v[8:11]
	v_mfma_f32_16x16x32_bf16 v[8:11], v[178:181], v[216:219], v[8:11]
	v_mfma_f32_16x16x32_bf16 v[4:7], v[182:185], v[212:215], v[4:7]
	v_mfma_f32_16x16x32_bf16 v[4:7], v[208:211], v[216:219], v[4:7]
	v_mfma_f32_16x16x32_bf16 v[32:35], v[174:177], v[220:223], v[32:35]
	v_mfma_f32_16x16x32_bf16 v[32:35], v[178:181], v[224:227], v[32:35]
	v_mfma_f32_16x16x32_bf16 v[28:31], v[182:185], v[220:223], v[28:31]
	v_mfma_f32_16x16x32_bf16 v[28:31], v[208:211], v[224:227], v[28:31]
	v_mfma_f32_16x16x32_bf16 v[56:59], v[174:177], v[228:231], v[56:59]
	v_mfma_f32_16x16x32_bf16 v[56:59], v[178:181], v[232:235], v[56:59]
	v_mfma_f32_16x16x32_bf16 v[52:55], v[182:185], v[228:231], v[52:55]
	v_mfma_f32_16x16x32_bf16 v[52:55], v[208:211], v[232:235], v[52:55]
	s_setprio 2
	s_barrier
; #define PG8_STAGE(bufoff, gbase, voff) do { _Pragma("unroll") for (int _i = 0; _i < 2; ++_i) \
;         __builtin_amdgcn_global_load_lds((const unsigned*)((const char*)(gbase) + (voff)[_i]), (LAS unsigned*)(lds + (bufoff) + ldsw + _i * 8192), 16, 0, 0); } while (0)
; #define PG8_LDA(dst, b, h) do { _Pragma("unroll") for (int m = 0; m < 4; ++m) _Pragma("unroll") for (int k = 0; k < 2; ++k) dst[m][k] = *(const LAS bf16x8*)(lds + PG8_SA(b, h) + aoff + m * 2048 + k * 1024); } while (0)
; #define PG8_MMA(ai, bj, At, Bt) do { __builtin_amdgcn_s_setprio(1); _Pragma("unroll") for (int m = 0; m < 4; ++m) _Pragma("unroll") for (int n = 0; n < 2; ++n) _Pragma("unroll") for (int k = 0; k < 2; ++k) \
;         acc[ai][bj][m][n] = __builtin_amdgcn_mfma_f32_16x16x32_bf16(Bt[n][k], At[m][k], acc[ai][bj][m][n], 0, 0, 0); __builtin_amdgcn_s_setprio(0); } while (0)
; #define PG8_WAIT_V(n) asm volatile("s_waitcnt vmcnt(" #n ")" ::: "memory")
; #define PG8_WAIT_L(n) asm volatile("s_waitcnt lgkmcnt(" #n ")" ::: "memory")
; #define PG8_BAR __builtin_amdgcn_s_barrier()
; #define PG8_SCHED __builtin_amdgcn_sched_barrier(0)
; template <class Epi, class Sched, bool ALIGN_EPI = true>
; __device__ __forceinline__ void gemm_phase(LAS unsigned char* lds, const Gemm g, const Sched& S, const Epi& E) {
;     ...
;             PG8_WAIT_V(8); PG8_WAIT_L(0); PG8_BAR; PG8_MMA(0, 0, At, B0); PG8_MMA(0, 1, At, B1); PG8_BAR; PG8_SCHED;
;             PG8_LDA(At, 1, 1); PG8_STAGE(PG8_SB(1, 0), b3, voffB); PG8_STAGE(PG8_SB(1, 1), b3 + hB, voffB); PG8_STAGE(PG8_SA(1, 0), a3, voffA);
;             PG8_WAIT_V(8); PG8_WAIT_L(0); PG8_BAR; PG8_MMA(1, 0, At, B0); PG8_MMA(1, 1, At, B1); PG8_BAR; PG8_SCHED;
;         }
	v_mfma_f32_16x16x32_bf16 v[80:83], v[174:177], v[236:239], v[80:83]
	v_mfma_f32_16x16x32_bf16 v[80:83], v[178:181], v[240:243], v[80:83]
	v_mfma_f32_16x16x32_bf16 v[76:79], v[182:185], v[236:239], v[76:79]
	v_mfma_f32_16x16x32_bf16 v[76:79], v[208:211], v[240:243], v[76:79]
	s_setprio 0
	s_add_i32 s10, s25, s67
	v_lshl_add_u64 v[162:163], v[244:245], 0, s[86:87]
	s_mov_b32 m0, s10
	ds_read_b128 v[212:215], v197 offset:49152
	ds_read_b128 v[216:219], v197 offset:50176
	ds_read_b128 v[220:223], v197 offset:51200
	ds_read_b128 v[224:227], v197 offset:52224
	ds_read_b128 v[228:231], v197 offset:53248
	ds_read_b128 v[232:235], v197 offset:54272
	ds_read_b128 v[236:239], v197 offset:55296
	ds_read_b128 v[240:243], v197 offset:56320
	global_load_lds_dwordx4 v[162:163], off
	s_add_i32 m0, s10, 0x2000
	s_add_u32 s10, s62, 0x80080
	v_lshl_add_u64 v[162:163], v[246:247], 0, s[86:87]
	s_addc_u32 s11, s63, 0
	s_add_i32 s25, s26, s67
	global_load_lds_dwordx4 v[162:163], off
	v_lshl_add_u64 v[162:163], s[10:11], 0, v[2:3]
	s_mov_b32 m0, s25
	v_lshl_add_u64 v[160:161], v[160:161], 0, s[86:87]
	global_load_lds_dwordx4 v[162:163], off
	v_lshl_add_u64 v[162:163], s[10:11], 0, v[150:151]
	s_add_i32 m0, s25, 0x2000
	s_nop 0
	global_load_lds_dwordx4 v[162:163], off
	v_lshl_add_u64 v[162:163], v[248:249], 0, s[86:87]
	s_mov_b32 m0, s79
	s_nop 0
	global_load_lds_dwordx4 v[162:163], off
	s_mov_b32 m0, s80
	s_nop 0
	global_load_lds_dwordx4 v[160:161], off
	s_waitcnt vmcnt(8)
	s_waitcnt lgkmcnt(0)
	s_barrier
	s_setprio 1
	s_waitcnt lgkmcnt(0)
	v_mfma_f32_16x16x32_bf16 v[120:123], v[136:139], v[212:215], v[120:123]
	v_mfma_f32_16x16x32_bf16 v[120:123], v[140:143], v[216:219], v[120:123]
	v_mfma_f32_16x16x32_bf16 v[116:119], v[144:147], v[212:215], v[116:119]
	v_mfma_f32_16x16x32_bf16 v[116:119], v[170:173], v[216:219], v[116:119]
	v_mfma_f32_16x16x32_bf16 v[96:99], v[136:139], v[220:223], v[96:99]
	v_mfma_f32_16x16x32_bf16 v[96:99], v[140:143], v[224:227], v[96:99]
	v_mfma_f32_16x16x32_bf16 v[92:95], v[144:147], v[220:223], v[92:95]
	v_mfma_f32_16x16x32_bf16 v[92:95], v[170:173], v[224:227], v[92:95]
	v_mfma_f32_16x16x32_bf16 v[64:67], v[136:139], v[228:231], v[64:67]
	v_mfma_f32_16x16x32_bf16 v[64:67], v[140:143], v[232:235], v[64:67]
	v_mfma_f32_16x16x32_bf16 v[60:63], v[144:147], v[228:231], v[60:63]
	v_mfma_f32_16x16x32_bf16 v[60:63], v[170:173], v[232:235], v[60:63]
	v_mfma_f32_16x16x32_bf16 v[24:27], v[136:139], v[236:239], v[24:27]
	v_mfma_f32_16x16x32_bf16 v[24:27], v[140:143], v[240:243], v[24:27]
	v_mfma_f32_16x16x32_bf16 v[20:23], v[144:147], v[236:239], v[20:23]
	v_mfma_f32_16x16x32_bf16 v[20:23], v[170:173], v[240:243], v[20:23]
	s_setprio 0
	s_setprio 1
	v_mfma_f32_16x16x32_bf16 v[112:115], v[174:177], v[212:215], v[112:115]
	v_mfma_f32_16x16x32_bf16 v[112:115], v[178:181], v[216:219], v[112:115]
	v_mfma_f32_16x16x32_bf16 v[108:111], v[182:185], v[212:215], v[108:111]
	v_mfma_f32_16x16x32_bf16 v[108:111], v[208:211], v[216:219], v[108:111]
	v_mfma_f32_16x16x32_bf16 v[88:91], v[174:177], v[220:223], v[88:91]
	v_mfma_f32_16x16x32_bf16 v[88:91], v[178:181], v[224:227], v[88:91]
	v_mfma_f32_16x16x32_bf16 v[84:87], v[182:185], v[220:223], v[84:87]
	v_mfma_f32_16x16x32_bf16 v[84:87], v[208:211], v[224:227], v[84:87]
	v_mfma_f32_16x16x32_bf16 v[48:51], v[174:177], v[228:231], v[48:51]
	v_mfma_f32_16x16x32_bf16 v[48:51], v[178:181], v[232:235], v[48:51]
	v_mfma_f32_16x16x32_bf16 v[44:47], v[182:185], v[228:231], v[44:47]
	v_mfma_f32_16x16x32_bf16 v[44:47], v[208:211], v[232:235], v[44:47]
	s_setprio 2
	s_barrier
	v_mfma_f32_16x16x32_bf16 v[16:19], v[174:177], v[236:239], v[16:19]
	v_mfma_f32_16x16x32_bf16 v[16:19], v[178:181], v[240:243], v[16:19]
	v_mfma_f32_16x16x32_bf16 v[12:15], v[182:185], v[236:239], v[12:15]
	v_mfma_f32_16x16x32_bf16 v[12:15], v[208:211], v[240:243], v[12:15]
	s_setprio 0
	s_add_i32 s24, s24, 2
	s_cmp_gt_u32 s24, 29
	s_mov_b64 s[10:11], vcc
	s_cbranch_scc1 .Lpeel_exit_667

; #define PG8_BAR __builtin_amdgcn_s_barrier()
; template <class Epi, class Sched, bool ALIGN_EPI = true>
; __device__ __forceinline__ void gemm_phase(LAS unsigned char* lds, const Gemm g, const Sched& S, const Epi& E) {
;     ...
;         if constexpr (ALIGN_EPI) { if (wr == 0) PG8_BAR; }
.Lpeel_exit_667:
	s_and_b64 vcc, exec, s[44:45]
	s_cbranch_vccz .LBB0_670
	s_barrier

;     __device__ bool next(int i, Unit& u) const { if (i >= 2) return false; const int x = c & 7, j = c >> 3; u.pm = 32 * i + 4 * x + (j & 3); u.pn = j >> 2; return true; }
; #define PG8_STAGE(bufoff, gbase, voff) do { _Pragma("unroll") for (int _i = 0; _i < 2; ++_i) \
;         __builtin_amdgcn_global_load_lds((const unsigned*)((const char*)(gbase) + (voff)[_i]), (LAS unsigned*)(lds + (bufoff) + ldsw + _i * 8192), 16, 0, 0); } while (0)
; #define PG8_WAIT_V(n) asm volatile("s_waitcnt vmcnt(" #n ")" ::: "memory")
; #define PG8_WAIT_L(n) asm volatile("s_waitcnt lgkmcnt(" #n ")" ::: "memory")
; #define PG8_BAR __builtin_amdgcn_s_barrier()
;     __device__ __forceinline__ void operator()(f32x4 (&acc)[2][2][4][2], const Unit& u, int wr, int wc, int fr_, int fq_, int wid, int lane_) const {
;     ...
;             const int t = wid * 64 + lane, kind = t >> 6, pr = t & 63, bj = kind >> 2, tap = kind & 3;
;             const float* src = (tap < 3) ? (cw + (size_t)tap * FF2 + bj * FF + u.pn * 128 + 2 * pr) : (cb + bj * FF + u.pn * 128 + 2 * pr);
;             const f32x2 wv = *(const f32x2*)src;
; template <class Epi, class Sched, bool ALIGN_EPI = true>
; __device__ __forceinline__ void gemm_phase(LAS unsigned char* lds, const Gemm g, const Sched& S, const Epi& E) {
;     ...
;         const bool has_next = S.next(ui + 1, nxt);
;         const char* nA = has_next ? (const char*)g.A + ((size_t)nxt.pm * BM * g.lda + (size_t)nxt.pn * g.a_pn_off) * 2 : cA; const char* nB = has_next ? (const char*)g.Bt + (size_t)nxt.pn * BM * g.ldb * 2 : cB;
;         for (int t = 0; t < nt; t += 2) {
;             const bool last = (t == nt - 2);
;             const char* a1 = cA + (size_t)(t + 1) * kstep;
;             const char* a2 = last ? nA : cA + (size_t)(t + 2) * kstep; const char* b2 = last ? nB : cB + (size_t)(t + 2) * kstep;
;             const char* a3 = a2 + kstep; const char* b3 = b2 + kstep;
;             PG8_LDB(B0, 0, 0); PG8_LDB(B1, 0, 1); PG8_SCHED; PG8_LDA(At, 0, 0); PG8_STAGE(PG8_SA(1, 1), a1 + hA, voffA);
;             PG8_WAIT_V(8); PG8_WAIT_L(0); PG8_BAR; PG8_MMA(0, 0, At, B0); PG8_MMA(0, 1, At, B1); PG8_BAR; PG8_SCHED;
;             PG8_LDA(At, 0, 1); PG8_STAGE(PG8_SB(0, 0), b2, voffB); PG8_STAGE(PG8_SB(0, 1), b2 + hB, voffB); PG8_STAGE(PG8_SA(0, 0), a2, voffA);
;             PG8_WAIT_V(8); PG8_WAIT_L(0); PG8_BAR; PG8_MMA(1, 0, At, B0); PG8_MMA(1, 1, At, B1); PG8_BAR; PG8_SCHED;
.LBB0_827:
	s_ashr_i32 s39, s38, 31
	s_lshl_b64 s[16:17], s[38:39], 20
	s_add_u32 s40, s46, s16
	s_addc_u32 s41, s47, s17
	s_and_b64 s[16:17], s[4:5], exec
	s_cselect_b32 s16, s41, s7
	s_cselect_b32 s17, s40, s6
	s_ashr_i32 s15, s14, 31
	s_lshl_b64 s[18:19], s[14:15], 20
	s_add_u32 s42, s53, s18
	s_addc_u32 s43, s60, s19
	s_and_b64 s[18:19], s[4:5], exec
	s_cselect_b32 s15, s43, s45
	s_cselect_b32 s18, s42, s44
	s_add_u32 s6, s6, 0x80080
	s_addc_u32 s7, s7, 0
	s_add_u32 s19, s44, 0x100
	s_addc_u32 s24, s45, 0
	s_mov_b32 s25, -2
	v_add_u32_e32 v228, s77, v158
	v_ashrrev_i32_e32 v229, 6, v228
	v_and_b32_e32 v230, 3, v229
	v_lshrrev_b32_e32 v231, 8, v228
	v_mul_u32_u24_e32 v228, 0x2c00, v230
	v_lshlrev_b32_e32 v228, 2, v228
	v_mov_b32_e32 v229, 0
	v_lshl_add_u64 v[232:233], s[2:3], 0, v[228:229]
	v_mov_b32_e32 v228, s9
	v_cmp_eq_u32_e32 vcc, 3, v230
	v_mul_i32_i24_e32 v234, 0x1600, v231
	v_ashrrev_i32_e32 v235, 31, v234
	v_cndmask_b32_e32 v233, v233, v228, vcc
	v_mov_b32_e32 v228, s8
	v_cndmask_b32_e32 v232, v232, v228, vcc
	v_lshl_add_u64 v[232:233], v[234:235], 2, v[232:233]
	s_lshl_b32 s26, s82, 7
	s_ashr_i32 s27, s26, 31
	v_lshl_add_u64 v[232:233], s[26:27], 2, v[232:233]
	v_and_b32_e32 v228, 63, v158
	v_lshlrev_b32_e32 v228, 3, v228
	v_mov_b32_e32 v229, 0
	v_lshl_add_u64 v[232:233], v[232:233], 0, v[228:229]
	global_load_dwordx2 v[226:227], v[232:233], off
	s_add_u32 s26, s6, 0xfff80080
	s_addc_u32 s27, s7, -1
	s_add_i32 s30, 0, 0x10000
	s_cmp_eq_u32 s25, 28
	s_cselect_b32 s59, s16, s27
	s_cselect_b32 s58, s17, s26
	v_add_u32_e32 v2, s30, v204
	s_cselect_b32 s45, s15, s24
	s_cselect_b32 s44, s18, s19
	s_add_i32 s31, 0, 0x14000
	ds_read_b128 v[132:135], v2
	ds_read_b128 v[136:139], v2 offset:1024
	ds_read_b128 v[140:143], v2 offset:2048
	ds_read_b128 v[144:147], v2 offset:3072
	v_add_u32_e32 v2, s31, v204
	ds_read_b128 v[148:151], v2
	ds_read_b128 v[152:155], v2 offset:1024
	ds_read_b128 v[174:177], v2 offset:2048
	ds_read_b128 v[178:181], v2 offset:3072
	v_lshl_add_u64 v[156:157], s[6:7], 0, v[170:171]
	s_add_i32 m0, s62, 0xc000
	ds_read_b128 v[182:185], v205
	ds_read_b128 v[186:189], v205 offset:1024
	ds_read_b128 v[190:193], v205 offset:2048
	ds_read_b128 v[194:197], v205 offset:3072
	ds_read_b128 v[206:209], v205 offset:4096
	ds_read_b128 v[210:213], v205 offset:5120
	ds_read_b128 v[214:217], v205 offset:6144
	ds_read_b128 v[218:221], v205 offset:7168
	global_load_lds_dwordx4 v[156:157], off
	v_lshl_add_u64 v[156:157], s[6:7], 0, v[172:173]
	s_add_i32 m0, s62, 0xe000
	s_nop 0
	global_load_lds_dwordx4 v[156:157], off
	s_waitcnt vmcnt(8)
	s_waitcnt lgkmcnt(0)
	s_barrier
	s_setprio 1
	s_waitcnt lgkmcnt(0)
	v_mfma_f32_16x16x32_bf16 v[116:119], v[132:135], v[182:185], 0
	v_mfma_f32_16x16x32_bf16 v[116:119], v[136:139], v[186:189], v[116:119]
	v_mfma_f32_16x16x32_bf16 v[100:103], v[140:143], v[182:185], 0
	v_mfma_f32_16x16x32_bf16 v[100:103], v[144:147], v[186:189], v[100:103]
	v_mfma_f32_16x16x32_bf16 v[108:111], v[132:135], v[190:193], 0
	v_mfma_f32_16x16x32_bf16 v[108:111], v[136:139], v[194:197], v[108:111]
	v_mfma_f32_16x16x32_bf16 v[96:99], v[140:143], v[190:193], 0
	v_mfma_f32_16x16x32_bf16 v[96:99], v[144:147], v[194:197], v[96:99]
	v_mfma_f32_16x16x32_bf16 v[88:91], v[132:135], v[206:209], 0
	v_mfma_f32_16x16x32_bf16 v[88:91], v[136:139], v[210:213], v[88:91]
	v_mfma_f32_16x16x32_bf16 v[84:87], v[140:143], v[206:209], 0
	v_mfma_f32_16x16x32_bf16 v[84:87], v[144:147], v[210:213], v[84:87]
	v_mfma_f32_16x16x32_bf16 v[72:75], v[132:135], v[214:217], 0
	v_mfma_f32_16x16x32_bf16 v[72:75], v[136:139], v[218:221], v[72:75]
	v_mfma_f32_16x16x32_bf16 v[80:83], v[140:143], v[214:217], 0
	v_mfma_f32_16x16x32_bf16 v[80:83], v[144:147], v[218:221], v[80:83]
	s_setprio 0
	s_setprio 1
	v_mfma_f32_16x16x32_bf16 v[128:131], v[148:151], v[182:185], 0
	v_mfma_f32_16x16x32_bf16 v[128:131], v[152:155], v[186:189], v[128:131]
	v_mfma_f32_16x16x32_bf16 v[44:47], v[174:177], v[182:185], 0
	v_mfma_f32_16x16x32_bf16 v[44:47], v[178:181], v[186:189], v[44:47]
	v_mfma_f32_16x16x32_bf16 v[124:127], v[148:151], v[190:193], 0
	v_mfma_f32_16x16x32_bf16 v[124:127], v[152:155], v[194:197], v[124:127]
	v_mfma_f32_16x16x32_bf16 v[36:39], v[174:177], v[190:193], 0
	v_mfma_f32_16x16x32_bf16 v[36:39], v[178:181], v[194:197], v[36:39]
	v_mfma_f32_16x16x32_bf16 v[120:123], v[148:151], v[206:209], 0
	v_mfma_f32_16x16x32_bf16 v[120:123], v[152:155], v[210:213], v[120:123]
	v_mfma_f32_16x16x32_bf16 v[32:35], v[174:177], v[206:209], 0
	v_mfma_f32_16x16x32_bf16 v[32:35], v[178:181], v[210:213], v[32:35]
	s_setprio 2
	s_barrier
	v_mfma_f32_16x16x32_bf16 v[112:115], v[148:151], v[214:217], 0
	v_mfma_f32_16x16x32_bf16 v[112:115], v[152:155], v[218:221], v[112:115]
	v_mfma_f32_16x16x32_bf16 v[28:31], v[174:177], v[214:217], 0
	v_mfma_f32_16x16x32_bf16 v[28:31], v[178:181], v[218:221], v[28:31]
	s_setprio 0
	s_add_i32 s26, s30, s61
	v_lshl_add_u64 v[156:157], s[44:45], 0, v[166:167]
	s_mov_b32 m0, s26
	ds_read_b128 v[182:185], v205 offset:16384
	ds_read_b128 v[186:189], v205 offset:17408
	ds_read_b128 v[190:193], v205 offset:18432
	ds_read_b128 v[194:197], v205 offset:19456
	ds_read_b128 v[206:209], v205 offset:20480
	ds_read_b128 v[210:213], v205 offset:21504
	ds_read_b128 v[214:217], v205 offset:22528
	ds_read_b128 v[218:221], v205 offset:23552
	global_load_lds_dwordx4 v[156:157], off
	s_add_i32 m0, s26, 0x2000
	s_add_u32 s26, s44, 0x80000
	v_lshl_add_u64 v[160:161], s[44:45], 0, v[0:1]
	s_addc_u32 s27, s45, 0
	s_add_i32 s30, s31, s61
	global_load_lds_dwordx4 v[160:161], off
	v_lshl_add_u64 v[162:163], s[26:27], 0, v[166:167]
	s_mov_b32 m0, s30
	v_lshl_add_u64 v[222:223], s[58:59], 0, v[164:165]
	global_load_lds_dwordx4 v[162:163], off
	v_lshl_add_u64 v[162:163], s[26:27], 0, v[0:1]
	s_add_i32 m0, s30, 0x2000
	s_nop 0
	global_load_lds_dwordx4 v[162:163], off
	v_lshl_add_u64 v[162:163], s[58:59], 0, v[168:169]
	s_mov_b32 m0, s62
	s_nop 0
	global_load_lds_dwordx4 v[162:163], off
	s_mov_b32 m0, s63
	s_nop 0
	global_load_lds_dwordx4 v[222:223], off
	s_waitcnt vmcnt(8)
	s_waitcnt lgkmcnt(0)
	s_barrier
; #define PG8_STAGE(bufoff, gbase, voff) do { _Pragma("unroll") for (int _i = 0; _i < 2; ++_i) \
;         __builtin_amdgcn_global_load_lds((const unsigned*)((const char*)(gbase) + (voff)[_i]), (LAS unsigned*)(lds + (bufoff) + ldsw + _i * 8192), 16, 0, 0); } while (0)
; #define PG8_LDA(dst, b, h) do { _Pragma("unroll") for (int m = 0; m < 4; ++m) _Pragma("unroll") for (int k = 0; k < 2; ++k) dst[m][k] = *(const LAS bf16x8*)(lds + PG8_SA(b, h) + aoff + m * 2048 + k * 1024); } while (0)
; #define PG8_LDB(dst, b, h) do { _Pragma("unroll") for (int n = 0; n < 2; ++n) _Pragma("unroll") for (int k = 0; k < 2; ++k) dst[n][k] = *(const LAS bf16x8*)(lds + PG8_SB(b, h) + boff + n * 2048 + k * 1024); } while (0)
; #define PG8_MMA(ai, bj, At, Bt) do { __builtin_amdgcn_s_setprio(1); _Pragma("unroll") for (int m = 0; m < 4; ++m) _Pragma("unroll") for (int n = 0; n < 2; ++n) _Pragma("unroll") for (int k = 0; k < 2; ++k) \
;         acc[ai][bj][m][n] = __builtin_amdgcn_mfma_f32_16x16x32_bf16(Bt[n][k], At[m][k], acc[ai][bj][m][n], 0, 0, 0); __builtin_amdgcn_s_setprio(0); } while (0)
; #define PG8_WAIT_V(n) asm volatile("s_waitcnt vmcnt(" #n ")" ::: "memory")
; #define PG8_WAIT_L(n) asm volatile("s_waitcnt lgkmcnt(" #n ")" ::: "memory")
; #define PG8_BAR __builtin_amdgcn_s_barrier()
; #define PG8_SCHED __builtin_amdgcn_sched_barrier(0)
; template <class Epi, class Sched, bool ALIGN_EPI = true>
; __device__ __forceinline__ void gemm_phase(LAS unsigned char* lds, const Gemm g, const Sched& S, const Epi& E) {
;     ...
;             PG8_WAIT_V(8); PG8_WAIT_L(0); PG8_BAR; PG8_MMA(1, 0, At, B0); PG8_MMA(1, 1, At, B1); PG8_BAR; PG8_SCHED;
;             PG8_LDB(B0, 1, 0); PG8_LDB(B1, 1, 1); PG8_SCHED; PG8_LDA(At, 1, 0); PG8_STAGE(PG8_SA(0, 1), a2 + hA, voffA);
;             PG8_WAIT_V(8); PG8_WAIT_L(0); PG8_BAR; PG8_MMA(0, 0, At, B0); PG8_MMA(0, 1, At, B1); PG8_BAR; PG8_SCHED;
	s_setprio 1
	s_waitcnt lgkmcnt(0)
	v_mfma_f32_16x16x32_bf16 v[60:63], v[132:135], v[182:185], 0
	v_mfma_f32_16x16x32_bf16 v[60:63], v[136:139], v[186:189], v[60:63]
	v_mfma_f32_16x16x32_bf16 v[68:71], v[140:143], v[182:185], 0
	v_mfma_f32_16x16x32_bf16 v[68:71], v[144:147], v[186:189], v[68:71]
	v_mfma_f32_16x16x32_bf16 v[40:43], v[132:135], v[190:193], 0
	v_mfma_f32_16x16x32_bf16 v[40:43], v[136:139], v[194:197], v[40:43]
	v_mfma_f32_16x16x32_bf16 v[64:67], v[140:143], v[190:193], 0
	v_mfma_f32_16x16x32_bf16 v[64:67], v[144:147], v[194:197], v[64:67]
	v_mfma_f32_16x16x32_bf16 v[24:27], v[132:135], v[206:209], 0
	v_mfma_f32_16x16x32_bf16 v[24:27], v[136:139], v[210:213], v[24:27]
	v_mfma_f32_16x16x32_bf16 v[56:59], v[140:143], v[206:209], 0
	v_mfma_f32_16x16x32_bf16 v[56:59], v[144:147], v[210:213], v[56:59]
	v_mfma_f32_16x16x32_bf16 v[12:15], v[132:135], v[214:217], 0
	v_mfma_f32_16x16x32_bf16 v[12:15], v[136:139], v[218:221], v[12:15]
	v_mfma_f32_16x16x32_bf16 v[48:51], v[140:143], v[214:217], 0
	v_mfma_f32_16x16x32_bf16 v[48:51], v[144:147], v[218:221], v[48:51]
	s_setprio 0
	s_setprio 1
	v_mfma_f32_16x16x32_bf16 v[104:107], v[148:151], v[182:185], 0
	v_mfma_f32_16x16x32_bf16 v[104:107], v[152:155], v[186:189], v[104:107]
	v_mfma_f32_16x16x32_bf16 v[20:23], v[174:177], v[182:185], 0
	v_mfma_f32_16x16x32_bf16 v[20:23], v[178:181], v[186:189], v[20:23]
	v_mfma_f32_16x16x32_bf16 v[92:95], v[148:151], v[190:193], 0
	v_mfma_f32_16x16x32_bf16 v[92:95], v[152:155], v[194:197], v[92:95]
	v_mfma_f32_16x16x32_bf16 v[16:19], v[174:177], v[190:193], 0
	v_mfma_f32_16x16x32_bf16 v[16:19], v[178:181], v[194:197], v[16:19]
	v_mfma_f32_16x16x32_bf16 v[76:79], v[148:151], v[206:209], 0
	v_mfma_f32_16x16x32_bf16 v[76:79], v[152:155], v[210:213], v[76:79]
	v_mfma_f32_16x16x32_bf16 v[8:11], v[174:177], v[206:209], 0
	v_mfma_f32_16x16x32_bf16 v[8:11], v[178:181], v[210:213], v[8:11]
	s_setprio 2
	s_barrier
	v_mfma_f32_16x16x32_bf16 v[52:55], v[148:151], v[214:217], 0
	v_mfma_f32_16x16x32_bf16 v[52:55], v[152:155], v[218:221], v[52:55]
	v_mfma_f32_16x16x32_bf16 v[4:7], v[174:177], v[214:217], 0
	v_mfma_f32_16x16x32_bf16 v[4:7], v[178:181], v[218:221], v[4:7]
	s_setprio 0
	s_add_i32 s30, 0, 0x18000
	v_add_u32_e32 v2, s30, v204
	s_add_i32 s31, 0, 0x1c000
	ds_read_b128 v[132:135], v2
	ds_read_b128 v[136:139], v2 offset:1024
	ds_read_b128 v[140:143], v2 offset:2048
	ds_read_b128 v[144:147], v2 offset:3072
	v_add_u32_e32 v2, s31, v204
	ds_read_b128 v[148:151], v2
	ds_read_b128 v[152:155], v2 offset:1024
	ds_read_b128 v[174:177], v2 offset:2048
	ds_read_b128 v[178:181], v2 offset:3072
	s_add_u32 s26, s58, 0x80000
	s_addc_u32 s27, s59, 0
	s_mov_b32 m0, s64
	v_lshl_add_u64 v[224:225], s[26:27], 0, v[168:169]
	ds_read_b128 v[182:185], v205 offset:32768
	ds_read_b128 v[186:189], v205 offset:33792
	ds_read_b128 v[190:193], v205 offset:34816
	ds_read_b128 v[194:197], v205 offset:35840
	ds_read_b128 v[206:209], v205 offset:36864
	ds_read_b128 v[210:213], v205 offset:37888
	ds_read_b128 v[214:217], v205 offset:38912
	ds_read_b128 v[218:221], v205 offset:39936
	global_load_lds_dwordx4 v[224:225], off
	v_lshl_add_u64 v[224:225], s[26:27], 0, v[164:165]
	s_mov_b32 m0, s65
	s_nop 0
	global_load_lds_dwordx4 v[224:225], off
	s_waitcnt vmcnt(8)
	s_waitcnt lgkmcnt(0)
	s_barrier
	s_setprio 1
	s_waitcnt lgkmcnt(0)
	v_mfma_f32_16x16x32_bf16 v[116:119], v[132:135], v[182:185], v[116:119]
	v_mfma_f32_16x16x32_bf16 v[116:119], v[136:139], v[186:189], v[116:119]
	v_mfma_f32_16x16x32_bf16 v[100:103], v[140:143], v[182:185], v[100:103]
	v_mfma_f32_16x16x32_bf16 v[100:103], v[144:147], v[186:189], v[100:103]
	v_mfma_f32_16x16x32_bf16 v[108:111], v[132:135], v[190:193], v[108:111]
	v_mfma_f32_16x16x32_bf16 v[108:111], v[136:139], v[194:197], v[108:111]
	v_mfma_f32_16x16x32_bf16 v[96:99], v[140:143], v[190:193], v[96:99]
	v_mfma_f32_16x16x32_bf16 v[96:99], v[144:147], v[194:197], v[96:99]
	v_mfma_f32_16x16x32_bf16 v[88:91], v[132:135], v[206:209], v[88:91]
	v_mfma_f32_16x16x32_bf16 v[88:91], v[136:139], v[210:213], v[88:91]
	v_mfma_f32_16x16x32_bf16 v[84:87], v[140:143], v[206:209], v[84:87]
	v_mfma_f32_16x16x32_bf16 v[84:87], v[144:147], v[210:213], v[84:87]
	v_mfma_f32_16x16x32_bf16 v[72:75], v[132:135], v[214:217], v[72:75]
	v_mfma_f32_16x16x32_bf16 v[72:75], v[136:139], v[218:221], v[72:75]
	v_mfma_f32_16x16x32_bf16 v[80:83], v[140:143], v[214:217], v[80:83]
	v_mfma_f32_16x16x32_bf16 v[80:83], v[144:147], v[218:221], v[80:83]
	s_setprio 0
	s_setprio 1
	v_mfma_f32_16x16x32_bf16 v[128:131], v[148:151], v[182:185], v[128:131]
	v_mfma_f32_16x16x32_bf16 v[128:131], v[152:155], v[186:189], v[128:131]
	v_mfma_f32_16x16x32_bf16 v[44:47], v[174:177], v[182:185], v[44:47]
	v_mfma_f32_16x16x32_bf16 v[44:47], v[178:181], v[186:189], v[44:47]
	v_mfma_f32_16x16x32_bf16 v[124:127], v[148:151], v[190:193], v[124:127]
	v_mfma_f32_16x16x32_bf16 v[124:127], v[152:155], v[194:197], v[124:127]
	v_mfma_f32_16x16x32_bf16 v[36:39], v[174:177], v[190:193], v[36:39]
	v_mfma_f32_16x16x32_bf16 v[36:39], v[178:181], v[194:197], v[36:39]
	v_mfma_f32_16x16x32_bf16 v[120:123], v[148:151], v[206:209], v[120:123]
	v_mfma_f32_16x16x32_bf16 v[120:123], v[152:155], v[210:213], v[120:123]
	v_mfma_f32_16x16x32_bf16 v[32:35], v[174:177], v[206:209], v[32:35]
	v_mfma_f32_16x16x32_bf16 v[32:35], v[178:181], v[210:213], v[32:35]
	s_setprio 2
	s_barrier
; #define PG8_STAGE(bufoff, gbase, voff) do { _Pragma("unroll") for (int _i = 0; _i < 2; ++_i) \
;         __builtin_amdgcn_global_load_lds((const unsigned*)((const char*)(gbase) + (voff)[_i]), (LAS unsigned*)(lds + (bufoff) + ldsw + _i * 8192), 16, 0, 0); } while (0)
; #define PG8_LDA(dst, b, h) do { _Pragma("unroll") for (int m = 0; m < 4; ++m) _Pragma("unroll") for (int k = 0; k < 2; ++k) dst[m][k] = *(const LAS bf16x8*)(lds + PG8_SA(b, h) + aoff + m * 2048 + k * 1024); } while (0)
; #define PG8_MMA(ai, bj, At, Bt) do { __builtin_amdgcn_s_setprio(1); _Pragma("unroll") for (int m = 0; m < 4; ++m) _Pragma("unroll") for (int n = 0; n < 2; ++n) _Pragma("unroll") for (int k = 0; k < 2; ++k) \
;         acc[ai][bj][m][n] = __builtin_amdgcn_mfma_f32_16x16x32_bf16(Bt[n][k], At[m][k], acc[ai][bj][m][n], 0, 0, 0); __builtin_amdgcn_s_setprio(0); } while (0)
; #define PG8_WAIT_V(n) asm volatile("s_waitcnt vmcnt(" #n ")" ::: "memory")
; #define PG8_WAIT_L(n) asm volatile("s_waitcnt lgkmcnt(" #n ")" ::: "memory")
; #define PG8_BAR __builtin_amdgcn_s_barrier()
; #define PG8_SCHED __builtin_amdgcn_sched_barrier(0)
; template <class Epi, class Sched, bool ALIGN_EPI = true>
; __device__ __forceinline__ void gemm_phase(LAS unsigned char* lds, const Gemm g, const Sched& S, const Epi& E) {
;     ...
;             PG8_WAIT_V(8); PG8_WAIT_L(0); PG8_BAR; PG8_MMA(0, 0, At, B0); PG8_MMA(0, 1, At, B1); PG8_BAR; PG8_SCHED;
;             PG8_LDA(At, 1, 1); PG8_STAGE(PG8_SB(1, 0), b3, voffB); PG8_STAGE(PG8_SB(1, 1), b3 + hB, voffB); PG8_STAGE(PG8_SA(1, 0), a3, voffA);
;             PG8_WAIT_V(8); PG8_WAIT_L(0); PG8_BAR; PG8_MMA(1, 0, At, B0); PG8_MMA(1, 1, At, B1); PG8_BAR; PG8_SCHED;
;         }
	v_mfma_f32_16x16x32_bf16 v[112:115], v[148:151], v[214:217], v[112:115]
	v_mfma_f32_16x16x32_bf16 v[112:115], v[152:155], v[218:221], v[112:115]
	v_mfma_f32_16x16x32_bf16 v[28:31], v[174:177], v[214:217], v[28:31]
	v_mfma_f32_16x16x32_bf16 v[28:31], v[178:181], v[218:221], v[28:31]
	s_setprio 0
	s_add_i32 s26, s30, s61
	v_lshl_add_u64 v[156:157], v[156:157], 0, s[86:87]
	s_mov_b32 m0, s26
	ds_read_b128 v[182:185], v205 offset:49152
	ds_read_b128 v[186:189], v205 offset:50176
	ds_read_b128 v[190:193], v205 offset:51200
	ds_read_b128 v[194:197], v205 offset:52224
	ds_read_b128 v[206:209], v205 offset:53248
	ds_read_b128 v[210:213], v205 offset:54272
	ds_read_b128 v[214:217], v205 offset:55296
	ds_read_b128 v[218:221], v205 offset:56320
	global_load_lds_dwordx4 v[156:157], off
	s_add_i32 m0, s26, 0x2000
	s_add_u32 s26, s44, 0x80080
	v_lshl_add_u64 v[156:157], v[160:161], 0, s[86:87]
	s_addc_u32 s27, s45, 0
	s_add_i32 s30, s31, s61
	global_load_lds_dwordx4 v[156:157], off
	v_lshl_add_u64 v[156:157], s[26:27], 0, v[166:167]
	s_mov_b32 m0, s30
	s_nop 0
	global_load_lds_dwordx4 v[156:157], off
	v_lshl_add_u64 v[156:157], s[26:27], 0, v[0:1]
	s_add_i32 m0, s30, 0x2000
	s_nop 0
	global_load_lds_dwordx4 v[156:157], off
	v_lshl_add_u64 v[156:157], v[162:163], 0, s[86:87]
	s_mov_b32 m0, s75
	s_nop 0
	global_load_lds_dwordx4 v[156:157], off
	v_lshl_add_u64 v[156:157], v[222:223], 0, s[86:87]
	s_mov_b32 m0, s76
	s_nop 0
	global_load_lds_dwordx4 v[156:157], off
	s_waitcnt vmcnt(8)
	s_waitcnt lgkmcnt(0)
	s_barrier
	s_setprio 1
	s_waitcnt lgkmcnt(0)
	v_mfma_f32_16x16x32_bf16 v[60:63], v[132:135], v[182:185], v[60:63]
	v_mfma_f32_16x16x32_bf16 v[60:63], v[136:139], v[186:189], v[60:63]
	v_mfma_f32_16x16x32_bf16 v[68:71], v[140:143], v[182:185], v[68:71]
	v_mfma_f32_16x16x32_bf16 v[68:71], v[144:147], v[186:189], v[68:71]
	v_mfma_f32_16x16x32_bf16 v[40:43], v[132:135], v[190:193], v[40:43]
	v_mfma_f32_16x16x32_bf16 v[40:43], v[136:139], v[194:197], v[40:43]
	v_mfma_f32_16x16x32_bf16 v[64:67], v[140:143], v[190:193], v[64:67]
	v_mfma_f32_16x16x32_bf16 v[64:67], v[144:147], v[194:197], v[64:67]
	v_mfma_f32_16x16x32_bf16 v[24:27], v[132:135], v[206:209], v[24:27]
	v_mfma_f32_16x16x32_bf16 v[24:27], v[136:139], v[210:213], v[24:27]
	v_mfma_f32_16x16x32_bf16 v[56:59], v[140:143], v[206:209], v[56:59]
	v_mfma_f32_16x16x32_bf16 v[56:59], v[144:147], v[210:213], v[56:59]
	v_mfma_f32_16x16x32_bf16 v[12:15], v[132:135], v[214:217], v[12:15]
	v_mfma_f32_16x16x32_bf16 v[12:15], v[136:139], v[218:221], v[12:15]
	v_mfma_f32_16x16x32_bf16 v[48:51], v[140:143], v[214:217], v[48:51]
	v_mfma_f32_16x16x32_bf16 v[48:51], v[144:147], v[218:221], v[48:51]
	s_setprio 0
	s_setprio 1
	v_mfma_f32_16x16x32_bf16 v[104:107], v[148:151], v[182:185], v[104:107]
	v_mfma_f32_16x16x32_bf16 v[104:107], v[152:155], v[186:189], v[104:107]
	v_mfma_f32_16x16x32_bf16 v[20:23], v[174:177], v[182:185], v[20:23]
	v_mfma_f32_16x16x32_bf16 v[20:23], v[178:181], v[186:189], v[20:23]
	v_mfma_f32_16x16x32_bf16 v[92:95], v[148:151], v[190:193], v[92:95]
	v_mfma_f32_16x16x32_bf16 v[92:95], v[152:155], v[194:197], v[92:95]
	v_mfma_f32_16x16x32_bf16 v[16:19], v[174:177], v[190:193], v[16:19]
	v_mfma_f32_16x16x32_bf16 v[16:19], v[178:181], v[194:197], v[16:19]
	v_mfma_f32_16x16x32_bf16 v[76:79], v[148:151], v[206:209], v[76:79]
	v_mfma_f32_16x16x32_bf16 v[76:79], v[152:155], v[210:213], v[76:79]
	v_mfma_f32_16x16x32_bf16 v[8:11], v[174:177], v[206:209], v[8:11]
	v_mfma_f32_16x16x32_bf16 v[8:11], v[178:181], v[210:213], v[8:11]
	s_setprio 2
	s_barrier
	v_mfma_f32_16x16x32_bf16 v[52:55], v[148:151], v[214:217], v[52:55]
	v_mfma_f32_16x16x32_bf16 v[52:55], v[152:155], v[218:221], v[52:55]
	v_mfma_f32_16x16x32_bf16 v[4:7], v[174:177], v[214:217], v[4:7]
	v_mfma_f32_16x16x32_bf16 v[4:7], v[178:181], v[218:221], v[4:7]
	s_setprio 0
	s_add_i32 s25, s25, 2
	s_add_u32 s6, s6, 0x100
	s_addc_u32 s7, s7, 0
	s_add_u32 s19, s19, 0x100
	s_addc_u32 s24, s24, 0
	s_cmp_gt_u32 s25, 29
	s_cbranch_scc1 .Lpeel_exit_828

; #define PG8_BAR __builtin_amdgcn_s_barrier()
; template <class Epi, class Sched, bool ALIGN_EPI = true>
; __device__ __forceinline__ void gemm_phase(LAS unsigned char* lds, const Gemm g, const Sched& S, const Epi& E) {
;     ...
;         if constexpr (ALIGN_EPI) { if (wr == 0) PG8_BAR; }
.Lpeel_exit_828:
	s_and_b64 vcc, exec, s[12:13]
	s_cbranch_vccz .LBB0_831
	s_barrier

;     __device__ bool next(int i, Unit& u) const { if (i >= 2) return false; const int x = c & 7, j = c >> 3; u.pm = 32 * i + 4 * x + (j & 3); u.pn = j >> 2; return true; }
; #define PG8_STAGE(bufoff, gbase, voff) do { _Pragma("unroll") for (int _i = 0; _i < 2; ++_i) \
;         __builtin_amdgcn_global_load_lds((const unsigned*)((const char*)(gbase) + (voff)[_i]), (LAS unsigned*)(lds + (bufoff) + ldsw + _i * 8192), 16, 0, 0); } while (0)
; #define PG8_LDA(dst, b, h) do { _Pragma("unroll") for (int m = 0; m < 4; ++m) _Pragma("unroll") for (int k = 0; k < 2; ++k) dst[m][k] = *(const LAS bf16x8*)(lds + PG8_SA(b, h) + aoff + m * 2048 + k * 1024); } while (0)
; #define PG8_LDB(dst, b, h) do { _Pragma("unroll") for (int n = 0; n < 2; ++n) _Pragma("unroll") for (int k = 0; k < 2; ++k) dst[n][k] = *(const LAS bf16x8*)(lds + PG8_SB(b, h) + boff + n * 2048 + k * 1024); } while (0)
; #define PG8_WAIT_V(n) asm volatile("s_waitcnt vmcnt(" #n ")" ::: "memory")
; #define PG8_WAIT_L(n) asm volatile("s_waitcnt lgkmcnt(" #n ")" ::: "memory")
; #define PG8_BAR __builtin_amdgcn_s_barrier()
; template <class Epi, class Sched, bool ALIGN_EPI = true>
; __device__ __forceinline__ void gemm_phase(LAS unsigned char* lds, const Gemm g, const Sched& S, const Epi& E) {
;     ...
;         const bool has_next = S.next(ui + 1, nxt);
;         const char* nA = has_next ? (const char*)g.A + ((size_t)nxt.pm * BM * g.lda + (size_t)nxt.pn * g.a_pn_off) * 2 : cA; const char* nB = has_next ? (const char*)g.Bt + (size_t)nxt.pn * BM * g.ldb * 2 : cB;
;         for (int t = 0; t < nt; t += 2) {
;             const bool last = (t == nt - 2);
;             const char* a1 = cA + (size_t)(t + 1) * kstep;
;             const char* a2 = last ? nA : cA + (size_t)(t + 2) * kstep; const char* b2 = last ? nB : cB + (size_t)(t + 2) * kstep;
;             const char* a3 = a2 + kstep; const char* b3 = b2 + kstep;
;             PG8_LDB(B0, 0, 0); PG8_LDB(B1, 0, 1); PG8_SCHED; PG8_LDA(At, 0, 0); PG8_STAGE(PG8_SA(1, 1), a1 + hA, voffA);
;             PG8_WAIT_V(8); PG8_WAIT_L(0); PG8_BAR; PG8_MMA(0, 0, At, B0); PG8_MMA(0, 1, At, B1); PG8_BAR; PG8_SCHED;
;             PG8_LDA(At, 0, 1); PG8_STAGE(PG8_SB(0, 0), b2, voffB); PG8_STAGE(PG8_SB(0, 1), b2 + hB, voffB); PG8_STAGE(PG8_SA(0, 0), a2, voffA);
;             PG8_WAIT_V(8); PG8_WAIT_L(0); PG8_BAR; PG8_MMA(1, 0, At, B0); PG8_MMA(1, 1, At, B1); PG8_BAR; PG8_SCHED;
.LBB0_1110:
	s_add_u32 s16, s10, 0x100
	s_addc_u32 s17, s11, 0
	s_add_u32 s10, s10, 0x160080
	s_addc_u32 s11, s11, 0
	v_lshl_add_u64 v[132:133], s[10:11], 0, v[168:169]
	v_lshl_add_u64 v[134:135], s[10:11], 0, v[170:171]
	s_mov_b32 s18, -2
	s_mov_b64 s[10:11], 0
	s_add_u32 vcc_lo, s10, 0x100
	s_addc_u32 vcc_hi, s11, 0
	s_add_u32 s19, s16, s10
	s_addc_u32 s24, s17, s11
	s_add_i32 s25, 0, 0x10000
	s_cmpk_eq_i32 s18, 0x54
	s_cselect_b32 s65, s61, s24
	s_cselect_b32 s24, 0, vcc_lo
	s_cselect_b32 s64, s60, s19
	s_cselect_b32 s19, 0, vcc_hi
	s_add_u32 s62, s2, s24
	v_add_u32_e32 v160, s25, v188
	s_addc_u32 s63, s3, s19
	s_add_i32 s19, 0, 0x14000
	ds_read_b128 v[136:139], v160
	ds_read_b128 v[140:143], v160 offset:1024
	ds_read_b128 v[144:147], v160 offset:2048
	ds_read_b128 v[172:175], v160 offset:3072
	v_add_u32_e32 v160, s19, v188
	ds_read_b128 v[176:179], v160
	ds_read_b128 v[180:183], v160 offset:1024
	ds_read_b128 v[184:187], v160 offset:2048
	ds_read_b128 v[208:211], v160 offset:3072
	v_lshl_add_u64 v[160:161], v[132:133], 0, s[10:11]
	s_add_i32 m0, s67, 0xc000
	ds_read_b128 v[212:215], v197
	ds_read_b128 v[216:219], v197 offset:1024
	ds_read_b128 v[220:223], v197 offset:2048
	ds_read_b128 v[224:227], v197 offset:3072
	ds_read_b128 v[228:231], v197 offset:4096
	ds_read_b128 v[232:235], v197 offset:5120
	ds_read_b128 v[236:239], v197 offset:6144
	ds_read_b128 v[240:243], v197 offset:7168
	global_load_lds_dwordx4 v[160:161], off
	v_lshl_add_u64 v[160:161], v[134:135], 0, s[10:11]
	s_add_i32 m0, s67, 0xe000
	s_nop 0
	global_load_lds_dwordx4 v[160:161], off
	s_waitcnt vmcnt(8)
	s_waitcnt lgkmcnt(0)
	s_barrier
	s_setprio 1
	s_waitcnt lgkmcnt(0)
	v_mfma_f32_16x16x32_bf16 v[16:19], v[136:139], v[212:215], 0
	v_mfma_f32_16x16x32_bf16 v[16:19], v[140:143], v[216:219], v[16:19]
	v_mfma_f32_16x16x32_bf16 v[12:15], v[144:147], v[212:215], 0
	v_mfma_f32_16x16x32_bf16 v[12:15], v[172:175], v[216:219], v[12:15]
	v_mfma_f32_16x16x32_bf16 v[56:59], v[136:139], v[220:223], 0
	v_mfma_f32_16x16x32_bf16 v[56:59], v[140:143], v[224:227], v[56:59]
	v_mfma_f32_16x16x32_bf16 v[52:55], v[144:147], v[220:223], 0
	v_mfma_f32_16x16x32_bf16 v[52:55], v[172:175], v[224:227], v[52:55]
	v_mfma_f32_16x16x32_bf16 v[88:91], v[136:139], v[228:231], 0
	v_mfma_f32_16x16x32_bf16 v[88:91], v[140:143], v[232:235], v[88:91]
	v_mfma_f32_16x16x32_bf16 v[76:79], v[144:147], v[228:231], 0
	v_mfma_f32_16x16x32_bf16 v[76:79], v[172:175], v[232:235], v[76:79]
	v_mfma_f32_16x16x32_bf16 v[112:115], v[136:139], v[236:239], 0
	v_mfma_f32_16x16x32_bf16 v[112:115], v[140:143], v[240:243], v[112:115]
	v_mfma_f32_16x16x32_bf16 v[108:111], v[144:147], v[236:239], 0
	v_mfma_f32_16x16x32_bf16 v[108:111], v[172:175], v[240:243], v[108:111]
	s_setprio 0
	s_setprio 1
	v_mfma_f32_16x16x32_bf16 v[8:11], v[176:179], v[212:215], 0
	v_mfma_f32_16x16x32_bf16 v[8:11], v[180:183], v[216:219], v[8:11]
	v_mfma_f32_16x16x32_bf16 v[4:7], v[184:187], v[212:215], 0
	v_mfma_f32_16x16x32_bf16 v[4:7], v[208:211], v[216:219], v[4:7]
	v_mfma_f32_16x16x32_bf16 v[40:43], v[176:179], v[220:223], 0
	v_mfma_f32_16x16x32_bf16 v[40:43], v[180:183], v[224:227], v[40:43]
	v_mfma_f32_16x16x32_bf16 v[36:39], v[184:187], v[220:223], 0
	v_mfma_f32_16x16x32_bf16 v[36:39], v[208:211], v[224:227], v[36:39]
	v_mfma_f32_16x16x32_bf16 v[64:67], v[176:179], v[228:231], 0
	v_mfma_f32_16x16x32_bf16 v[64:67], v[180:183], v[232:235], v[64:67]
	v_mfma_f32_16x16x32_bf16 v[60:63], v[184:187], v[228:231], 0
	v_mfma_f32_16x16x32_bf16 v[60:63], v[208:211], v[232:235], v[60:63]
	s_setprio 2
	s_barrier
	v_mfma_f32_16x16x32_bf16 v[96:99], v[176:179], v[236:239], 0
	v_mfma_f32_16x16x32_bf16 v[96:99], v[180:183], v[240:243], v[96:99]
	v_mfma_f32_16x16x32_bf16 v[92:95], v[184:187], v[236:239], 0
	v_mfma_f32_16x16x32_bf16 v[92:95], v[208:211], v[240:243], v[92:95]
	s_setprio 0
	s_add_i32 s10, s25, s66
	v_lshl_add_u64 v[160:161], s[62:63], 0, v[2:3]
	s_mov_b32 m0, s10
	ds_read_b128 v[212:215], v197 offset:16384
	ds_read_b128 v[216:219], v197 offset:17408
	ds_read_b128 v[220:223], v197 offset:18432
	ds_read_b128 v[224:227], v197 offset:19456
	ds_read_b128 v[228:231], v197 offset:20480
	ds_read_b128 v[232:235], v197 offset:21504
	ds_read_b128 v[236:239], v197 offset:22528
	ds_read_b128 v[240:243], v197 offset:23552
	global_load_lds_dwordx4 v[160:161], off
	s_add_i32 m0, s10, 0x2000
	s_add_u32 s10, s62, 0x160000
	v_lshl_add_u64 v[162:163], s[62:63], 0, v[150:151]
	s_addc_u32 s11, s63, 0
	s_add_i32 s19, s19, s66
	global_load_lds_dwordx4 v[162:163], off
	v_lshl_add_u64 v[244:245], s[10:11], 0, v[2:3]
	s_mov_b32 m0, s19
	v_lshl_add_u64 v[246:247], s[64:65], 0, v[148:149]
	global_load_lds_dwordx4 v[244:245], off
	v_lshl_add_u64 v[244:245], s[10:11], 0, v[150:151]
	s_add_i32 m0, s19, 0x2000
	s_nop 0
	global_load_lds_dwordx4 v[244:245], off
	v_lshl_add_u64 v[244:245], s[64:65], 0, v[0:1]
	s_mov_b32 m0, s67
	s_nop 0
	global_load_lds_dwordx4 v[244:245], off
	s_mov_b32 m0, s75
	s_nop 0
	global_load_lds_dwordx4 v[246:247], off
	s_waitcnt vmcnt(8)
	s_waitcnt lgkmcnt(0)
	s_barrier
; #define PG8_STAGE(bufoff, gbase, voff) do { _Pragma("unroll") for (int _i = 0; _i < 2; ++_i) \
;         __builtin_amdgcn_global_load_lds((const unsigned*)((const char*)(gbase) + (voff)[_i]), (LAS unsigned*)(lds + (bufoff) + ldsw + _i * 8192), 16, 0, 0); } while (0)
; #define PG8_LDA(dst, b, h) do { _Pragma("unroll") for (int m = 0; m < 4; ++m) _Pragma("unroll") for (int k = 0; k < 2; ++k) dst[m][k] = *(const LAS bf16x8*)(lds + PG8_SA(b, h) + aoff + m * 2048 + k * 1024); } while (0)
; #define PG8_LDB(dst, b, h) do { _Pragma("unroll") for (int n = 0; n < 2; ++n) _Pragma("unroll") for (int k = 0; k < 2; ++k) dst[n][k] = *(const LAS bf16x8*)(lds + PG8_SB(b, h) + boff + n * 2048 + k * 1024); } while (0)
; #define PG8_MMA(ai, bj, At, Bt) do { __builtin_amdgcn_s_setprio(1); _Pragma("unroll") for (int m = 0; m < 4; ++m) _Pragma("unroll") for (int n = 0; n < 2; ++n) _Pragma("unroll") for (int k = 0; k < 2; ++k) \
;         acc[ai][bj][m][n] = __builtin_amdgcn_mfma_f32_16x16x32_bf16(Bt[n][k], At[m][k], acc[ai][bj][m][n], 0, 0, 0); __builtin_amdgcn_s_setprio(0); } while (0)
; #define PG8_WAIT_V(n) asm volatile("s_waitcnt vmcnt(" #n ")" ::: "memory")
; #define PG8_WAIT_L(n) asm volatile("s_waitcnt lgkmcnt(" #n ")" ::: "memory")
; #define PG8_BAR __builtin_amdgcn_s_barrier()
; #define PG8_SCHED __builtin_amdgcn_sched_barrier(0)
; template <class Epi, class Sched, bool ALIGN_EPI = true>
; __device__ __forceinline__ void gemm_phase(LAS unsigned char* lds, const Gemm g, const Sched& S, const Epi& E) {
;     ...
;             PG8_WAIT_V(8); PG8_WAIT_L(0); PG8_BAR; PG8_MMA(1, 0, At, B0); PG8_MMA(1, 1, At, B1); PG8_BAR; PG8_SCHED;
;             PG8_LDB(B0, 1, 0); PG8_LDB(B1, 1, 1); PG8_SCHED; PG8_LDA(At, 1, 0); PG8_STAGE(PG8_SA(0, 1), a2 + hA, voffA);
;             PG8_WAIT_V(8); PG8_WAIT_L(0); PG8_BAR; PG8_MMA(0, 0, At, B0); PG8_MMA(0, 1, At, B1); PG8_BAR; PG8_SCHED;
	s_setprio 1
	s_waitcnt lgkmcnt(0)
	v_mfma_f32_16x16x32_bf16 v[128:131], v[136:139], v[212:215], 0
	v_mfma_f32_16x16x32_bf16 v[128:131], v[140:143], v[216:219], v[128:131]
	v_mfma_f32_16x16x32_bf16 v[124:127], v[144:147], v[212:215], 0
	v_mfma_f32_16x16x32_bf16 v[124:127], v[172:175], v[216:219], v[124:127]
	v_mfma_f32_16x16x32_bf16 v[104:107], v[136:139], v[220:223], 0
	v_mfma_f32_16x16x32_bf16 v[104:107], v[140:143], v[224:227], v[104:107]
	v_mfma_f32_16x16x32_bf16 v[100:103], v[144:147], v[220:223], 0
	v_mfma_f32_16x16x32_bf16 v[100:103], v[172:175], v[224:227], v[100:103]
	v_mfma_f32_16x16x32_bf16 v[72:75], v[136:139], v[228:231], 0
	v_mfma_f32_16x16x32_bf16 v[72:75], v[140:143], v[232:235], v[72:75]
	v_mfma_f32_16x16x32_bf16 v[68:71], v[144:147], v[228:231], 0
	v_mfma_f32_16x16x32_bf16 v[68:71], v[172:175], v[232:235], v[68:71]
	v_mfma_f32_16x16x32_bf16 v[32:35], v[136:139], v[236:239], 0
	v_mfma_f32_16x16x32_bf16 v[32:35], v[140:143], v[240:243], v[32:35]
	v_mfma_f32_16x16x32_bf16 v[28:31], v[144:147], v[236:239], 0
	v_mfma_f32_16x16x32_bf16 v[28:31], v[172:175], v[240:243], v[28:31]
	s_setprio 0
	s_setprio 1
	v_mfma_f32_16x16x32_bf16 v[120:123], v[176:179], v[212:215], 0
	v_mfma_f32_16x16x32_bf16 v[120:123], v[180:183], v[216:219], v[120:123]
	v_mfma_f32_16x16x32_bf16 v[116:119], v[184:187], v[212:215], 0
	v_mfma_f32_16x16x32_bf16 v[116:119], v[208:211], v[216:219], v[116:119]
	v_mfma_f32_16x16x32_bf16 v[84:87], v[176:179], v[220:223], 0
	v_mfma_f32_16x16x32_bf16 v[84:87], v[180:183], v[224:227], v[84:87]
	v_mfma_f32_16x16x32_bf16 v[80:83], v[184:187], v[220:223], 0
	v_mfma_f32_16x16x32_bf16 v[80:83], v[208:211], v[224:227], v[80:83]
	v_mfma_f32_16x16x32_bf16 v[48:51], v[176:179], v[228:231], 0
	v_mfma_f32_16x16x32_bf16 v[48:51], v[180:183], v[232:235], v[48:51]
	v_mfma_f32_16x16x32_bf16 v[44:47], v[184:187], v[228:231], 0
	v_mfma_f32_16x16x32_bf16 v[44:47], v[208:211], v[232:235], v[44:47]
	s_setprio 2
	s_barrier
	v_mfma_f32_16x16x32_bf16 v[24:27], v[176:179], v[236:239], 0
	v_mfma_f32_16x16x32_bf16 v[24:27], v[180:183], v[240:243], v[24:27]
	v_mfma_f32_16x16x32_bf16 v[20:23], v[184:187], v[236:239], 0
	v_mfma_f32_16x16x32_bf16 v[20:23], v[208:211], v[240:243], v[20:23]
	s_setprio 0
	s_add_i32 s19, 0, 0x18000
	s_add_i32 s24, 0, 0x1c000
	v_add_u32_e32 v172, s19, v188
	v_add_u32_e32 v207, s24, v188
	ds_read_b128 v[136:139], v172
	ds_read_b128 v[140:143], v172 offset:1024
	ds_read_b128 v[144:147], v172 offset:2048
	ds_read_b128 v[172:175], v172 offset:3072
	ds_read_b128 v[176:179], v207
	ds_read_b128 v[180:183], v207 offset:1024
	ds_read_b128 v[184:187], v207 offset:2048
	ds_read_b128 v[208:211], v207 offset:3072
	s_add_u32 s10, s64, 0x160000
	s_addc_u32 s11, s65, 0
	s_mov_b32 m0, s76
	v_lshl_add_u64 v[248:249], s[10:11], 0, v[0:1]
	ds_read_b128 v[212:215], v197 offset:32768
	ds_read_b128 v[216:219], v197 offset:33792
	ds_read_b128 v[220:223], v197 offset:34816
	ds_read_b128 v[224:227], v197 offset:35840
	ds_read_b128 v[228:231], v197 offset:36864
	ds_read_b128 v[232:235], v197 offset:37888
	ds_read_b128 v[236:239], v197 offset:38912
	ds_read_b128 v[240:243], v197 offset:39936
	global_load_lds_dwordx4 v[248:249], off
	v_lshl_add_u64 v[248:249], s[10:11], 0, v[148:149]
	s_mov_b32 m0, s77
	s_nop 0
	global_load_lds_dwordx4 v[248:249], off
	s_waitcnt vmcnt(8)
	s_waitcnt lgkmcnt(0)
	s_barrier
	s_setprio 1
	s_waitcnt lgkmcnt(0)
	v_mfma_f32_16x16x32_bf16 v[16:19], v[136:139], v[212:215], v[16:19]
	v_mfma_f32_16x16x32_bf16 v[16:19], v[140:143], v[216:219], v[16:19]
	v_mfma_f32_16x16x32_bf16 v[12:15], v[144:147], v[212:215], v[12:15]
	v_mfma_f32_16x16x32_bf16 v[12:15], v[172:175], v[216:219], v[12:15]
	v_mfma_f32_16x16x32_bf16 v[56:59], v[136:139], v[220:223], v[56:59]
	v_mfma_f32_16x16x32_bf16 v[56:59], v[140:143], v[224:227], v[56:59]
	v_mfma_f32_16x16x32_bf16 v[52:55], v[144:147], v[220:223], v[52:55]
	v_mfma_f32_16x16x32_bf16 v[52:55], v[172:175], v[224:227], v[52:55]
	v_mfma_f32_16x16x32_bf16 v[88:91], v[136:139], v[228:231], v[88:91]
	v_mfma_f32_16x16x32_bf16 v[88:91], v[140:143], v[232:235], v[88:91]
	v_mfma_f32_16x16x32_bf16 v[76:79], v[144:147], v[228:231], v[76:79]
	v_mfma_f32_16x16x32_bf16 v[76:79], v[172:175], v[232:235], v[76:79]
	v_mfma_f32_16x16x32_bf16 v[112:115], v[136:139], v[236:239], v[112:115]
	v_mfma_f32_16x16x32_bf16 v[112:115], v[140:143], v[240:243], v[112:115]
	v_mfma_f32_16x16x32_bf16 v[108:111], v[144:147], v[236:239], v[108:111]
	v_mfma_f32_16x16x32_bf16 v[108:111], v[172:175], v[240:243], v[108:111]
	s_setprio 0
	s_setprio 1
	v_mfma_f32_16x16x32_bf16 v[8:11], v[176:179], v[212:215], v[8:11]
	v_mfma_f32_16x16x32_bf16 v[8:11], v[180:183], v[216:219], v[8:11]
	v_mfma_f32_16x16x32_bf16 v[4:7], v[184:187], v[212:215], v[4:7]
	v_mfma_f32_16x16x32_bf16 v[4:7], v[208:211], v[216:219], v[4:7]
	v_mfma_f32_16x16x32_bf16 v[40:43], v[176:179], v[220:223], v[40:43]
	v_mfma_f32_16x16x32_bf16 v[40:43], v[180:183], v[224:227], v[40:43]
	v_mfma_f32_16x16x32_bf16 v[36:39], v[184:187], v[220:223], v[36:39]
	v_mfma_f32_16x16x32_bf16 v[36:39], v[208:211], v[224:227], v[36:39]
	v_mfma_f32_16x16x32_bf16 v[64:67], v[176:179], v[228:231], v[64:67]
	v_mfma_f32_16x16x32_bf16 v[64:67], v[180:183], v[232:235], v[64:67]
	v_mfma_f32_16x16x32_bf16 v[60:63], v[184:187], v[228:231], v[60:63]
	v_mfma_f32_16x16x32_bf16 v[60:63], v[208:211], v[232:235], v[60:63]
	s_setprio 2
	s_barrier
; #define PG8_STAGE(bufoff, gbase, voff) do { _Pragma("unroll") for (int _i = 0; _i < 2; ++_i) \
;         __builtin_amdgcn_global_load_lds((const unsigned*)((const char*)(gbase) + (voff)[_i]), (LAS unsigned*)(lds + (bufoff) + ldsw + _i * 8192), 16, 0, 0); } while (0)
; #define PG8_LDA(dst, b, h) do { _Pragma("unroll") for (int m = 0; m < 4; ++m) _Pragma("unroll") for (int k = 0; k < 2; ++k) dst[m][k] = *(const LAS bf16x8*)(lds + PG8_SA(b, h) + aoff + m * 2048 + k * 1024); } while (0)
; #define PG8_MMA(ai, bj, At, Bt) do { __builtin_amdgcn_s_setprio(1); _Pragma("unroll") for (int m = 0; m < 4; ++m) _Pragma("unroll") for (int n = 0; n < 2; ++n) _Pragma("unroll") for (int k = 0; k < 2; ++k) \
;         acc[ai][bj][m][n] = __builtin_amdgcn_mfma_f32_16x16x32_bf16(Bt[n][k], At[m][k], acc[ai][bj][m][n], 0, 0, 0); __builtin_amdgcn_s_setprio(0); } while (0)
; #define PG8_WAIT_V(n) asm volatile("s_waitcnt vmcnt(" #n ")" ::: "memory")
; #define PG8_WAIT_L(n) asm volatile("s_waitcnt lgkmcnt(" #n ")" ::: "memory")
; #define PG8_BAR __builtin_amdgcn_s_barrier()
; #define PG8_SCHED __builtin_amdgcn_sched_barrier(0)
; template <class Epi, class Sched, bool ALIGN_EPI = true>
; __device__ __forceinline__ void gemm_phase(LAS unsigned char* lds, const Gemm g, const Sched& S, const Epi& E) {
;     ...
;             PG8_WAIT_V(8); PG8_WAIT_L(0); PG8_BAR; PG8_MMA(0, 0, At, B0); PG8_MMA(0, 1, At, B1); PG8_BAR; PG8_SCHED;
;             PG8_LDA(At, 1, 1); PG8_STAGE(PG8_SB(1, 0), b3, voffB); PG8_STAGE(PG8_SB(1, 1), b3 + hB, voffB); PG8_STAGE(PG8_SA(1, 0), a3, voffA);
;             PG8_WAIT_V(8); PG8_WAIT_L(0); PG8_BAR; PG8_MMA(1, 0, At, B0); PG8_MMA(1, 1, At, B1); PG8_BAR; PG8_SCHED;
;         }
	v_mfma_f32_16x16x32_bf16 v[96:99], v[176:179], v[236:239], v[96:99]
	v_mfma_f32_16x16x32_bf16 v[96:99], v[180:183], v[240:243], v[96:99]
	v_mfma_f32_16x16x32_bf16 v[92:95], v[184:187], v[236:239], v[92:95]
	v_mfma_f32_16x16x32_bf16 v[92:95], v[208:211], v[240:243], v[92:95]
	s_setprio 0
	s_add_i32 s10, s19, s66
	v_lshl_add_u64 v[160:161], v[160:161], 0, s[86:87]
	s_mov_b32 m0, s10
	ds_read_b128 v[212:215], v197 offset:49152
	ds_read_b128 v[216:219], v197 offset:50176
	ds_read_b128 v[220:223], v197 offset:51200
	ds_read_b128 v[224:227], v197 offset:52224
	ds_read_b128 v[228:231], v197 offset:53248
	ds_read_b128 v[232:235], v197 offset:54272
	ds_read_b128 v[236:239], v197 offset:55296
	ds_read_b128 v[240:243], v197 offset:56320
	global_load_lds_dwordx4 v[160:161], off
	s_add_i32 m0, s10, 0x2000
	s_add_u32 s10, s62, 0x160080
	v_lshl_add_u64 v[160:161], v[162:163], 0, s[86:87]
	s_addc_u32 s11, s63, 0
	s_add_i32 s19, s24, s66
	global_load_lds_dwordx4 v[160:161], off
	v_lshl_add_u64 v[160:161], s[10:11], 0, v[2:3]
	s_mov_b32 m0, s19
	s_nop 0
	global_load_lds_dwordx4 v[160:161], off
	v_lshl_add_u64 v[160:161], s[10:11], 0, v[150:151]
	s_add_i32 m0, s19, 0x2000
	s_nop 0
	global_load_lds_dwordx4 v[160:161], off
	v_lshl_add_u64 v[160:161], v[244:245], 0, s[86:87]
	s_mov_b32 m0, s80
	s_nop 0
	global_load_lds_dwordx4 v[160:161], off
	v_lshl_add_u64 v[160:161], v[246:247], 0, s[86:87]
	s_mov_b32 m0, s81
	s_nop 0
	global_load_lds_dwordx4 v[160:161], off
	s_waitcnt vmcnt(8)
	s_waitcnt lgkmcnt(0)
	s_barrier
	s_setprio 1
	s_waitcnt lgkmcnt(0)
	v_mfma_f32_16x16x32_bf16 v[128:131], v[136:139], v[212:215], v[128:131]
	v_mfma_f32_16x16x32_bf16 v[128:131], v[140:143], v[216:219], v[128:131]
	v_mfma_f32_16x16x32_bf16 v[124:127], v[144:147], v[212:215], v[124:127]
	v_mfma_f32_16x16x32_bf16 v[124:127], v[172:175], v[216:219], v[124:127]
	v_mfma_f32_16x16x32_bf16 v[104:107], v[136:139], v[220:223], v[104:107]
	v_mfma_f32_16x16x32_bf16 v[104:107], v[140:143], v[224:227], v[104:107]
	v_mfma_f32_16x16x32_bf16 v[100:103], v[144:147], v[220:223], v[100:103]
	v_mfma_f32_16x16x32_bf16 v[100:103], v[172:175], v[224:227], v[100:103]
	v_mfma_f32_16x16x32_bf16 v[72:75], v[136:139], v[228:231], v[72:75]
	v_mfma_f32_16x16x32_bf16 v[72:75], v[140:143], v[232:235], v[72:75]
	v_mfma_f32_16x16x32_bf16 v[68:71], v[144:147], v[228:231], v[68:71]
	v_mfma_f32_16x16x32_bf16 v[68:71], v[172:175], v[232:235], v[68:71]
	v_mfma_f32_16x16x32_bf16 v[32:35], v[136:139], v[236:239], v[32:35]
	v_mfma_f32_16x16x32_bf16 v[32:35], v[140:143], v[240:243], v[32:35]
	v_mfma_f32_16x16x32_bf16 v[28:31], v[144:147], v[236:239], v[28:31]
	v_mfma_f32_16x16x32_bf16 v[28:31], v[172:175], v[240:243], v[28:31]
	s_setprio 0
	s_setprio 1
	v_mfma_f32_16x16x32_bf16 v[120:123], v[176:179], v[212:215], v[120:123]
	v_mfma_f32_16x16x32_bf16 v[120:123], v[180:183], v[216:219], v[120:123]
	v_mfma_f32_16x16x32_bf16 v[116:119], v[184:187], v[212:215], v[116:119]
	v_mfma_f32_16x16x32_bf16 v[116:119], v[208:211], v[216:219], v[116:119]
	v_mfma_f32_16x16x32_bf16 v[84:87], v[176:179], v[220:223], v[84:87]
	v_mfma_f32_16x16x32_bf16 v[84:87], v[180:183], v[224:227], v[84:87]
	v_mfma_f32_16x16x32_bf16 v[80:83], v[184:187], v[220:223], v[80:83]
	v_mfma_f32_16x16x32_bf16 v[80:83], v[208:211], v[224:227], v[80:83]
	v_mfma_f32_16x16x32_bf16 v[48:51], v[176:179], v[228:231], v[48:51]
	v_mfma_f32_16x16x32_bf16 v[48:51], v[180:183], v[232:235], v[48:51]
	v_mfma_f32_16x16x32_bf16 v[44:47], v[184:187], v[228:231], v[44:47]
	v_mfma_f32_16x16x32_bf16 v[44:47], v[208:211], v[232:235], v[44:47]
	s_setprio 2
	s_barrier
	v_mfma_f32_16x16x32_bf16 v[24:27], v[176:179], v[236:239], v[24:27]
	v_mfma_f32_16x16x32_bf16 v[24:27], v[180:183], v[240:243], v[24:27]
	v_mfma_f32_16x16x32_bf16 v[20:23], v[184:187], v[236:239], v[20:23]
	v_mfma_f32_16x16x32_bf16 v[20:23], v[208:211], v[240:243], v[20:23]
	s_setprio 0
	s_add_i32 s18, s18, 2
	s_cmpk_gt_u32 s18, 0x55
	s_mov_b64 s[10:11], vcc
	s_cbranch_scc1 .Lpeel_exit_1111

; #define PG8_BAR __builtin_amdgcn_s_barrier()
; template <class Epi, class Sched, bool ALIGN_EPI = true>
; __device__ __forceinline__ void gemm_phase(LAS unsigned char* lds, const Gemm g, const Sched& S, const Epi& E) {
;     ...
;         if constexpr (ALIGN_EPI) { if (wr == 0) PG8_BAR; }
.Lpeel_exit_1111:
	s_and_b64 vcc, exec, s[42:43]
	s_cbranch_vccz .LBB0_1114
	s_barrier
